# EpiRes epilogues (G7 both paths, G9): residual loads batched 4 per row with counted vmcnt(3) instead of serialized load-vmcnt(0)-store chains
# speedup vs baseline: 1.0337x; 1.0208x over previous
; #define PG8_STAGE(bufoff, gbase, voff) do { _Pragma("unroll") for (int _i = 0; _i < 2; ++_i) \
;         __builtin_amdgcn_global_load_lds((const unsigned*)((const char*)(gbase) + (voff)[_i]), (LAS unsigned*)(lds + (bufoff) + ldsw + _i * 8192), 16, 0, 0); } while (0)
; #define PG8_LDA(dst, b, h) do { _Pragma("unroll") for (int m = 0; m < 4; ++m) _Pragma("unroll") for (int k = 0; k < 2; ++k) dst[m][k] = *(const LAS bf16x8*)(lds + PG8_SA(b, h) + aoff + m * 2048 + k * 1024); } while (0)
; #define PG8_LDB(dst, b, h) do { _Pragma("unroll") for (int n = 0; n < 2; ++n) _Pragma("unroll") for (int k = 0; k < 2; ++k) dst[n][k] = *(const LAS bf16x8*)(lds + PG8_SB(b, h) + boff + n * 2048 + k * 1024); } while (0)
; #define PG8_MMA(ai, bj, At, Bt) do { __builtin_amdgcn_s_setprio(1); _Pragma("unroll") for (int m = 0; m < 4; ++m) _Pragma("unroll") for (int n = 0; n < 2; ++n) _Pragma("unroll") for (int k = 0; k < 2; ++k) \
;         acc[ai][bj][m][n] = __builtin_amdgcn_mfma_f32_16x16x32_bf16(Bt[n][k], At[m][k], acc[ai][bj][m][n], 0, 0, 0); __builtin_amdgcn_s_setprio(0); } while (0)
; #define PG8_WAIT_V(n) asm volatile("s_waitcnt vmcnt(" #n ")" ::: "memory")
; #define PG8_WAIT_L(n) asm volatile("s_waitcnt lgkmcnt(" #n ")" ::: "memory")
; #define PG8_BAR __builtin_amdgcn_s_barrier()
; #define PG8_SCHED __builtin_amdgcn_sched_barrier(0)
; template <class Epi, class SchedT>
; DI void gemm_phase(LAS unsigned char* lds, const Gemm g, const SchedT& S, const Epi& E) {
;     ...
;             PG8_LDB(B0, 0, 0); PG8_SCHED; PG8_LDA(At, 0, 0); PG8_STAGE(PG8_SA(1, 1), a1 + hstepA, voffA);
;             PG8_WAIT_L(8); PG8_BAR; PG8_WAIT_L(0); PG8_MMA(0, 0, At, B0); PG8_BAR; PG8_SCHED;
;             PG8_LDB(B1, 0, 1); PG8_STAGE(PG8_SB(0, 0), b2, voffB);
;             PG8_BAR; PG8_WAIT_L(0); PG8_MMA(0, 1, At, B1); PG8_BAR;
;             PG8_LDA(At, 0, 1); PG8_STAGE(PG8_SA(0, 0), a2, voffA);
;             PG8_BAR; PG8_WAIT_L(0); PG8_MMA(1, 0, At, B0); PG8_BAR; PG8_SCHED;
;             PG8_STAGE(PG8_SB(0, 1), b2 + hstepB, voffB);
;             PG8_WAIT_V(6); PG8_BAR; PG8_MMA(1, 1, At, B1); PG8_BAR;
.LBB0_1447:
	s_add_u32 s20, s18, 0xfff80080
	s_addc_u32 s21, s19, -1
	s_add_i32 s47, 0, 0x10000
	v_add_u32_e32 v108, s47, v154
	ds_read_b128 v[100:103], v108
	ds_read_b128 v[104:107], v108 offset:1024
	ds_read_b128 v[118:121], v108 offset:2048
	ds_read_b128 v[146:149], v108 offset:3072
	s_cmp_eq_u32 s46, 28
	s_cselect_b32 s23, s9, s21
	s_cselect_b32 s22, s15, s20
	s_cselect_b32 s21, s7, s45
	s_cselect_b32 s20, s17, s33
	v_lshl_add_u64 v[108:109], s[18:19], 0, v[0:1]
	s_add_i32 m0, s35, 0xc000
	ds_read_b128 v[156:159], v155
	ds_read_b128 v[160:163], v155 offset:1024
	ds_read_b128 v[164:167], v155 offset:2048
	ds_read_b128 v[168:171], v155 offset:3072
	ds_read_b128 v[172:175], v155 offset:4096
	ds_read_b128 v[176:179], v155 offset:5120
	ds_read_b128 v[184:187], v155 offset:6144
	ds_read_b128 v[188:191], v155 offset:7168
	global_load_lds_dwordx4 v[108:109], off
	v_lshl_add_u64 v[108:109], s[18:19], 0, v[98:99]
	s_add_i32 m0, s35, 0xe000
	s_nop 0
	global_load_lds_dwordx4 v[108:109], off
	s_waitcnt lgkmcnt(8)
	s_barrier
	s_waitcnt lgkmcnt(0)
	s_setprio 1
	s_waitcnt lgkmcnt(0)
	v_mfma_f32_16x16x32_bf16 v[142:145], v[100:103], v[156:159], v[142:145]
	v_mfma_f32_16x16x32_bf16 v[138:141], v[118:121], v[156:159], v[138:141]
	v_mfma_f32_16x16x32_bf16 v[126:129], v[100:103], v[164:167], v[126:129]
	v_mfma_f32_16x16x32_bf16 v[122:125], v[118:121], v[164:167], v[122:125]
	v_mfma_f32_16x16x32_bf16 v[94:97], v[100:103], v[172:175], v[94:97]
	v_mfma_f32_16x16x32_bf16 v[90:93], v[118:121], v[172:175], v[90:93]
	v_mfma_f32_16x16x32_bf16 v[78:81], v[100:103], v[184:187], v[78:81]
	v_mfma_f32_16x16x32_bf16 v[74:77], v[118:121], v[184:187], v[74:77]
	v_mfma_f32_16x16x32_bf16 v[142:145], v[104:107], v[160:163], v[142:145]
	v_mfma_f32_16x16x32_bf16 v[138:141], v[146:149], v[160:163], v[138:141]
	v_mfma_f32_16x16x32_bf16 v[126:129], v[104:107], v[168:171], v[126:129]
	v_mfma_f32_16x16x32_bf16 v[122:125], v[146:149], v[168:171], v[122:125]
	v_mfma_f32_16x16x32_bf16 v[94:97], v[104:107], v[176:179], v[94:97]
	v_mfma_f32_16x16x32_bf16 v[90:93], v[146:149], v[176:179], v[90:93]
	v_mfma_f32_16x16x32_bf16 v[78:81], v[104:107], v[188:191], v[78:81]
	v_mfma_f32_16x16x32_bf16 v[74:77], v[146:149], v[188:191], v[74:77]
	s_setprio 0
	s_barrier
	s_add_i32 s52, 0, 0x14000
	s_add_i32 s47, s47, s28
	v_add_u32_e32 v108, s52, v154
	v_lshl_add_u64 v[150:151], s[20:21], 0, v[0:1]
	s_mov_b32 m0, s47
	ds_read_b128 v[202:205], v108
	ds_read_b128 v[206:209], v108 offset:1024
	ds_read_b128 v[210:213], v108 offset:2048
	ds_read_b128 v[214:217], v108 offset:3072
	global_load_lds_dwordx4 v[150:151], off
	v_lshl_add_u64 v[180:181], s[20:21], 0, v[98:99]
	s_add_i32 m0, s47, 0x2000
	s_nop 0
	global_load_lds_dwordx4 v[180:181], off
	s_barrier
	s_waitcnt lgkmcnt(0)
	s_setprio 1
	s_waitcnt lgkmcnt(0)
	v_mfma_f32_16x16x32_bf16 v[134:137], v[202:205], v[156:159], v[134:137]
	v_mfma_f32_16x16x32_bf16 v[130:133], v[210:213], v[156:159], v[130:133]
	v_mfma_f32_16x16x32_bf16 v[114:117], v[202:205], v[164:167], v[114:117]
	v_mfma_f32_16x16x32_bf16 v[108:111], v[210:213], v[164:167], v[110:113]
	v_mfma_f32_16x16x32_bf16 v[86:89], v[202:205], v[172:175], v[86:89]
	v_mfma_f32_16x16x32_bf16 v[82:85], v[210:213], v[172:175], v[82:85]
	v_mfma_f32_16x16x32_bf16 v[70:73], v[202:205], v[184:187], v[70:73]
	v_mfma_f32_16x16x32_bf16 v[66:69], v[210:213], v[184:187], v[66:69]
	v_mfma_f32_16x16x32_bf16 v[134:137], v[206:209], v[160:163], v[134:137]
	v_mfma_f32_16x16x32_bf16 v[130:133], v[214:217], v[160:163], v[130:133]
	v_mfma_f32_16x16x32_bf16 v[114:117], v[206:209], v[168:171], v[114:117]
	v_mfma_f32_16x16x32_bf16 v[108:111], v[214:217], v[168:171], v[108:111]
	v_mfma_f32_16x16x32_bf16 v[86:89], v[206:209], v[176:179], v[86:89]
	v_mfma_f32_16x16x32_bf16 v[82:85], v[214:217], v[176:179], v[82:85]
	v_mfma_f32_16x16x32_bf16 v[70:73], v[206:209], v[188:191], v[70:73]
	v_mfma_f32_16x16x32_bf16 v[66:69], v[214:217], v[188:191], v[66:69]
	s_setprio 0
	s_mov_b32 m0, s35
	v_lshl_add_u64 v[182:183], s[22:23], 0, v[0:1]
	s_barrier
	ds_read_b128 v[156:159], v155 offset:16384
	ds_read_b128 v[160:163], v155 offset:17408
	ds_read_b128 v[164:167], v155 offset:18432
	ds_read_b128 v[168:171], v155 offset:19456
	ds_read_b128 v[172:175], v155 offset:20480
	ds_read_b128 v[176:179], v155 offset:21504
	ds_read_b128 v[184:187], v155 offset:22528
	ds_read_b128 v[188:191], v155 offset:23552
	global_load_lds_dwordx4 v[182:183], off
	v_lshl_add_u64 v[194:195], s[22:23], 0, v[98:99]
	s_mov_b32 m0, s36
	s_nop 0
	global_load_lds_dwordx4 v[194:195], off
	s_barrier
	s_waitcnt lgkmcnt(0)
	s_setprio 1
	s_waitcnt lgkmcnt(0)
	v_mfma_f32_16x16x32_bf16 v[62:65], v[100:103], v[156:159], v[62:65]
	v_mfma_f32_16x16x32_bf16 v[58:61], v[118:121], v[156:159], v[58:61]
	v_mfma_f32_16x16x32_bf16 v[46:49], v[100:103], v[164:167], v[46:49]
	v_mfma_f32_16x16x32_bf16 v[42:45], v[118:121], v[164:167], v[42:45]
	v_mfma_f32_16x16x32_bf16 v[30:33], v[100:103], v[172:175], v[30:33]
	v_mfma_f32_16x16x32_bf16 v[26:29], v[118:121], v[172:175], v[26:29]
	v_mfma_f32_16x16x32_bf16 v[14:17], v[100:103], v[184:187], v[14:17]
	v_mfma_f32_16x16x32_bf16 v[10:13], v[118:121], v[184:187], v[10:13]
	v_mfma_f32_16x16x32_bf16 v[62:65], v[104:107], v[160:163], v[62:65]
	v_mfma_f32_16x16x32_bf16 v[58:61], v[146:149], v[160:163], v[58:61]
	v_mfma_f32_16x16x32_bf16 v[46:49], v[104:107], v[168:171], v[46:49]
	v_mfma_f32_16x16x32_bf16 v[42:45], v[146:149], v[168:171], v[42:45]
	v_mfma_f32_16x16x32_bf16 v[30:33], v[104:107], v[176:179], v[30:33]
	v_mfma_f32_16x16x32_bf16 v[26:29], v[146:149], v[176:179], v[26:29]
	v_mfma_f32_16x16x32_bf16 v[14:17], v[104:107], v[188:191], v[14:17]
	v_mfma_f32_16x16x32_bf16 v[10:13], v[146:149], v[188:191], v[10:13]
	s_setprio 0
	s_barrier
; #define PG8_STAGE(bufoff, gbase, voff) do { _Pragma("unroll") for (int _i = 0; _i < 2; ++_i) \
;         __builtin_amdgcn_global_load_lds((const unsigned*)((const char*)(gbase) + (voff)[_i]), (LAS unsigned*)(lds + (bufoff) + ldsw + _i * 8192), 16, 0, 0); } while (0)
; #define PG8_LDA(dst, b, h) do { _Pragma("unroll") for (int m = 0; m < 4; ++m) _Pragma("unroll") for (int k = 0; k < 2; ++k) dst[m][k] = *(const LAS bf16x8*)(lds + PG8_SA(b, h) + aoff + m * 2048 + k * 1024); } while (0)
; #define PG8_LDB(dst, b, h) do { _Pragma("unroll") for (int n = 0; n < 2; ++n) _Pragma("unroll") for (int k = 0; k < 2; ++k) dst[n][k] = *(const LAS bf16x8*)(lds + PG8_SB(b, h) + boff + n * 2048 + k * 1024); } while (0)
; #define PG8_MMA(ai, bj, At, Bt) do { __builtin_amdgcn_s_setprio(1); _Pragma("unroll") for (int m = 0; m < 4; ++m) _Pragma("unroll") for (int n = 0; n < 2; ++n) _Pragma("unroll") for (int k = 0; k < 2; ++k) \
;         acc[ai][bj][m][n] = __builtin_amdgcn_mfma_f32_16x16x32_bf16(Bt[n][k], At[m][k], acc[ai][bj][m][n], 0, 0, 0); __builtin_amdgcn_s_setprio(0); } while (0)
; #define PG8_WAIT_V(n) asm volatile("s_waitcnt vmcnt(" #n ")" ::: "memory")
; #define PG8_WAIT_L(n) asm volatile("s_waitcnt lgkmcnt(" #n ")" ::: "memory")
; #define PG8_BAR __builtin_amdgcn_s_barrier()
; #define PG8_SCHED __builtin_amdgcn_sched_barrier(0)
; template <class Epi, class SchedT>
; DI void gemm_phase(LAS unsigned char* lds, const Gemm g, const SchedT& S, const Epi& E) {
;     ...
;             PG8_STAGE(PG8_SB(0, 1), b2 + hstepB, voffB);
;             PG8_WAIT_V(6); PG8_BAR; PG8_MMA(1, 1, At, B1); PG8_BAR;
;             PG8_LDB(B0, 1, 0); PG8_SCHED; PG8_LDA(At, 1, 0); PG8_STAGE(PG8_SA(0, 1), a2 + hstepA, voffA);
;             PG8_WAIT_L(8); PG8_BAR; PG8_WAIT_L(0); PG8_MMA(0, 0, At, B0); PG8_BAR; PG8_SCHED;
;             PG8_LDB(B1, 1, 1); PG8_STAGE(PG8_SB(1, 0), b3, voffB);
;             PG8_BAR; PG8_WAIT_L(0); PG8_MMA(0, 1, At, B1); PG8_BAR;
;             PG8_LDA(At, 1, 1); PG8_STAGE(PG8_SA(1, 0), a3, voffA);
	s_add_u32 s48, s20, 0x80000
	s_addc_u32 s49, s21, 0
	s_add_i32 s47, s52, s28
	v_lshl_add_u64 v[100:101], s[48:49], 0, v[0:1]
	s_mov_b32 m0, s47
	s_nop 0
	global_load_lds_dwordx4 v[100:101], off
	v_lshl_add_u64 v[100:101], s[48:49], 0, v[98:99]
	s_add_i32 m0, s47, 0x2000
	s_nop 0
	global_load_lds_dwordx4 v[100:101], off
	s_waitcnt vmcnt(6)
	s_barrier
	s_setprio 1
	v_mfma_f32_16x16x32_bf16 v[54:57], v[202:205], v[156:159], v[54:57]
	v_mfma_f32_16x16x32_bf16 v[50:53], v[210:213], v[156:159], v[50:53]
	v_mfma_f32_16x16x32_bf16 v[38:41], v[202:205], v[164:167], v[38:41]
	v_mfma_f32_16x16x32_bf16 v[34:37], v[210:213], v[164:167], v[34:37]
	v_mfma_f32_16x16x32_bf16 v[22:25], v[202:205], v[172:175], v[22:25]
	v_mfma_f32_16x16x32_bf16 v[18:21], v[210:213], v[172:175], v[18:21]
	v_mfma_f32_16x16x32_bf16 v[6:9], v[202:205], v[184:187], v[6:9]
	v_mfma_f32_16x16x32_bf16 v[2:5], v[210:213], v[184:187], v[2:5]
	v_mfma_f32_16x16x32_bf16 v[54:57], v[206:209], v[160:163], v[54:57]
	v_mfma_f32_16x16x32_bf16 v[50:53], v[214:217], v[160:163], v[50:53]
	v_mfma_f32_16x16x32_bf16 v[38:41], v[206:209], v[168:171], v[38:41]
	v_mfma_f32_16x16x32_bf16 v[34:37], v[214:217], v[168:171], v[34:37]
	v_mfma_f32_16x16x32_bf16 v[22:25], v[206:209], v[176:179], v[22:25]
	v_mfma_f32_16x16x32_bf16 v[18:21], v[214:217], v[176:179], v[18:21]
	v_mfma_f32_16x16x32_bf16 v[6:9], v[206:209], v[188:191], v[6:9]
	v_mfma_f32_16x16x32_bf16 v[2:5], v[214:217], v[188:191], v[2:5]
	s_setprio 0
	s_add_i32 s47, 0, 0x18000
	v_add_u32_e32 v112, s47, v154
	s_barrier
	ds_read_b128 v[100:103], v112
	ds_read_b128 v[104:107], v112 offset:1024
	ds_read_b128 v[118:121], v112 offset:2048
	ds_read_b128 v[146:149], v112 offset:3072
	s_add_u32 s22, s22, 0x80000
	s_addc_u32 s23, s23, 0
	s_mov_b32 m0, s37
	v_lshl_add_u64 v[112:113], s[22:23], 0, v[0:1]
	ds_read_b128 v[156:159], v155 offset:32768
	ds_read_b128 v[160:163], v155 offset:33792
	ds_read_b128 v[164:167], v155 offset:34816
	ds_read_b128 v[168:171], v155 offset:35840
	ds_read_b128 v[172:175], v155 offset:36864
	ds_read_b128 v[176:179], v155 offset:37888
	ds_read_b128 v[184:187], v155 offset:38912
	ds_read_b128 v[188:191], v155 offset:39936
	global_load_lds_dwordx4 v[112:113], off
	v_lshl_add_u64 v[112:113], s[22:23], 0, v[98:99]
	s_mov_b32 m0, s40
	s_nop 0
	global_load_lds_dwordx4 v[112:113], off
	s_waitcnt lgkmcnt(8)
	s_barrier
	s_waitcnt lgkmcnt(0)
	s_setprio 1
	s_waitcnt lgkmcnt(0)
	v_mfma_f32_16x16x32_bf16 v[142:145], v[100:103], v[156:159], v[142:145]
	v_mfma_f32_16x16x32_bf16 v[138:141], v[118:121], v[156:159], v[138:141]
	v_mfma_f32_16x16x32_bf16 v[126:129], v[100:103], v[164:167], v[126:129]
	v_mfma_f32_16x16x32_bf16 v[122:125], v[118:121], v[164:167], v[122:125]
	v_mfma_f32_16x16x32_bf16 v[94:97], v[100:103], v[172:175], v[94:97]
	v_mfma_f32_16x16x32_bf16 v[90:93], v[118:121], v[172:175], v[90:93]
	v_mfma_f32_16x16x32_bf16 v[78:81], v[100:103], v[184:187], v[78:81]
	v_mfma_f32_16x16x32_bf16 v[74:77], v[118:121], v[184:187], v[74:77]
	v_mfma_f32_16x16x32_bf16 v[142:145], v[104:107], v[160:163], v[142:145]
	v_mfma_f32_16x16x32_bf16 v[138:141], v[146:149], v[160:163], v[138:141]
	v_mfma_f32_16x16x32_bf16 v[126:129], v[104:107], v[168:171], v[126:129]
	v_mfma_f32_16x16x32_bf16 v[122:125], v[146:149], v[168:171], v[122:125]
	v_mfma_f32_16x16x32_bf16 v[94:97], v[104:107], v[176:179], v[94:97]
	v_mfma_f32_16x16x32_bf16 v[90:93], v[146:149], v[176:179], v[90:93]
	v_mfma_f32_16x16x32_bf16 v[78:81], v[104:107], v[188:191], v[78:81]
	v_mfma_f32_16x16x32_bf16 v[74:77], v[146:149], v[188:191], v[74:77]
	s_setprio 0
	s_barrier
	s_add_i32 s22, 0, 0x1c000
	v_add_u32_e32 v112, s22, v154
	s_add_i32 s23, s47, s28
	ds_read_b128 v[202:205], v112
	ds_read_b128 v[206:209], v112 offset:1024
	ds_read_b128 v[210:213], v112 offset:2048
	ds_read_b128 v[214:217], v112 offset:3072
	v_lshl_add_u64 v[112:113], v[150:151], 0, s[90:91]
	s_mov_b32 m0, s23
	s_nop 0
	global_load_lds_dwordx4 v[112:113], off
	v_lshl_add_u64 v[112:113], v[180:181], 0, s[90:91]
	s_add_i32 m0, s23, 0x2000
	s_nop 0
	global_load_lds_dwordx4 v[112:113], off
	s_barrier
	s_waitcnt lgkmcnt(0)
	s_setprio 1
	s_waitcnt lgkmcnt(0)
	v_mfma_f32_16x16x32_bf16 v[134:137], v[202:205], v[156:159], v[134:137]
	v_mfma_f32_16x16x32_bf16 v[130:133], v[210:213], v[156:159], v[130:133]
	v_mfma_f32_16x16x32_bf16 v[112:115], v[202:205], v[164:167], v[114:117]
	v_mfma_f32_16x16x32_bf16 v[108:111], v[210:213], v[164:167], v[108:111]
	v_mfma_f32_16x16x32_bf16 v[86:89], v[202:205], v[172:175], v[86:89]
	v_mfma_f32_16x16x32_bf16 v[82:85], v[210:213], v[172:175], v[82:85]
	v_mfma_f32_16x16x32_bf16 v[70:73], v[202:205], v[184:187], v[70:73]
	v_mfma_f32_16x16x32_bf16 v[66:69], v[210:213], v[184:187], v[66:69]
	v_mfma_f32_16x16x32_bf16 v[134:137], v[206:209], v[160:163], v[134:137]
	v_mfma_f32_16x16x32_bf16 v[130:133], v[214:217], v[160:163], v[130:133]
	v_mfma_f32_16x16x32_bf16 v[114:117], v[206:209], v[168:171], v[112:115]
	v_mfma_f32_16x16x32_bf16 v[110:113], v[214:217], v[168:171], v[108:111]
	v_mfma_f32_16x16x32_bf16 v[86:89], v[206:209], v[176:179], v[86:89]
	v_mfma_f32_16x16x32_bf16 v[82:85], v[214:217], v[176:179], v[82:85]
	v_mfma_f32_16x16x32_bf16 v[70:73], v[206:209], v[188:191], v[70:73]
	v_mfma_f32_16x16x32_bf16 v[66:69], v[214:217], v[188:191], v[66:69]
	s_setprio 0
	s_mov_b32 m0, s42
	v_lshl_add_u64 v[108:109], v[182:183], 0, s[90:91]
	s_barrier
	ds_read_b128 v[156:159], v155 offset:49152
	ds_read_b128 v[160:163], v155 offset:50176
	ds_read_b128 v[164:167], v155 offset:51200
	ds_read_b128 v[168:171], v155 offset:52224
	ds_read_b128 v[172:175], v155 offset:53248
	ds_read_b128 v[176:179], v155 offset:54272
	ds_read_b128 v[184:187], v155 offset:55296
	ds_read_b128 v[188:191], v155 offset:56320
	global_load_lds_dwordx4 v[108:109], off
	v_lshl_add_u64 v[108:109], v[194:195], 0, s[90:91]
	s_mov_b32 m0, s43
	s_nop 0
	global_load_lds_dwordx4 v[108:109], off
	s_barrier
; DI unsigned pk2(float a, float b) { f32x2 v = {a, b}; bfv2 r = __builtin_convertvector(v, bfv2); return __builtin_bit_cast(unsigned, r); }
; #define PG8_STAGE(bufoff, gbase, voff) do { _Pragma("unroll") for (int _i = 0; _i < 2; ++_i) \
;         __builtin_amdgcn_global_load_lds((const unsigned*)((const char*)(gbase) + (voff)[_i]), (LAS unsigned*)(lds + (bufoff) + ldsw + _i * 8192), 16, 0, 0); } while (0)
; #define PG8_MMA(ai, bj, At, Bt) do { __builtin_amdgcn_s_setprio(1); _Pragma("unroll") for (int m = 0; m < 4; ++m) _Pragma("unroll") for (int n = 0; n < 2; ++n) _Pragma("unroll") for (int k = 0; k < 2; ++k) \
;         acc[ai][bj][m][n] = __builtin_amdgcn_mfma_f32_16x16x32_bf16(Bt[n][k], At[m][k], acc[ai][bj][m][n], 0, 0, 0); __builtin_amdgcn_s_setprio(0); } while (0)
; template <class Epi, class SchedT>
; DI void gemm_phase(LAS unsigned char* lds, const Gemm g, const SchedT& S, const Epi& E) {
;     ...
;             PG8_BAR; PG8_WAIT_L(0); PG8_MMA(1, 0, At, B0); PG8_BAR; PG8_SCHED;
;             PG8_STAGE(PG8_SB(1, 1), b3 + hstepB, voffB);
;             PG8_WAIT_V(6); PG8_BAR; PG8_MMA(1, 1, At, B1); PG8_BAR;
;     DI void operator()(AccRef acc, const Unit& u, int wr, int wc, int fr, int fq) const {
;         const int row0 = u.pm * 256; const int midx = row0 < ML ? (row0 >> 12) : 4;
;         const float* src = row0 < ML ? xl : (xc - (size_t)ML * D);
;         const float* gp = gate + (size_t)midx * 12288;
;         const int col0 = u.pn * 256 + wc * 32 + 4 * fq;
;         f32x4 gv[2][2];
; #pragma unroll
;         for (int bj = 0; bj < 2; ++bj)
; #pragma unroll
;             for (int n = 0; n < 2; ++n) gv[bj][n] = *(const f32x4*)(gp + col0 + bj * 128 + n * 16);
;         if (xb) {
; #pragma unroll
;             for (int ai = 0; ai < 2; ++ai)
; #pragma unroll
;                 for (int m = 0; m < 4; ++m) { const size_t off = (size_t)(row0 + wr * 64 + fr + ai * 128 + m * 16) * D + col0;
; #pragma unroll
;                     for (int bj = 0; bj < 2; ++bj)
; #pragma unroll
;                         for (int n = 0; n < 2; ++n) { const size_t o2 = off + bj * 128 + n * 16;
;                             const f32x4 r = bf4(*(const u32x2*)(xb + o2)) + gv[bj][n] * acc[ai][bj][m][n];
;                             u32x2 w; w.x = pk2(r[0], r[1]); w.y = pk2(r[2], r[3]); *(u32x2*)(out + o2) = w; }
;                     asm volatile("" ::: "memory"); }
	s_waitcnt lgkmcnt(0)
	s_setprio 1
	s_waitcnt lgkmcnt(0)
	v_mfma_f32_16x16x32_bf16 v[62:65], v[100:103], v[156:159], v[62:65]
	v_mfma_f32_16x16x32_bf16 v[58:61], v[118:121], v[156:159], v[58:61]
	v_mfma_f32_16x16x32_bf16 v[46:49], v[100:103], v[164:167], v[46:49]
	v_mfma_f32_16x16x32_bf16 v[42:45], v[118:121], v[164:167], v[42:45]
	v_mfma_f32_16x16x32_bf16 v[30:33], v[100:103], v[172:175], v[30:33]
	v_mfma_f32_16x16x32_bf16 v[26:29], v[118:121], v[172:175], v[26:29]
	v_mfma_f32_16x16x32_bf16 v[14:17], v[100:103], v[184:187], v[14:17]
	v_mfma_f32_16x16x32_bf16 v[10:13], v[118:121], v[184:187], v[10:13]
	v_mfma_f32_16x16x32_bf16 v[62:65], v[104:107], v[160:163], v[62:65]
	v_mfma_f32_16x16x32_bf16 v[58:61], v[146:149], v[160:163], v[58:61]
	v_mfma_f32_16x16x32_bf16 v[46:49], v[104:107], v[168:171], v[46:49]
	v_mfma_f32_16x16x32_bf16 v[42:45], v[146:149], v[168:171], v[42:45]
	v_mfma_f32_16x16x32_bf16 v[30:33], v[104:107], v[176:179], v[30:33]
	v_mfma_f32_16x16x32_bf16 v[26:29], v[146:149], v[176:179], v[26:29]
	v_mfma_f32_16x16x32_bf16 v[14:17], v[104:107], v[188:191], v[14:17]
	v_mfma_f32_16x16x32_bf16 v[10:13], v[146:149], v[188:191], v[10:13]
	s_setprio 0
	s_barrier
	s_add_u32 s20, s20, 0x80080
	s_addc_u32 s21, s21, 0
	s_add_i32 s22, s22, s28
	v_lshl_add_u64 v[100:101], s[20:21], 0, v[0:1]
	s_mov_b32 m0, s22
	s_nop 0
	global_load_lds_dwordx4 v[100:101], off
	v_lshl_add_u64 v[100:101], s[20:21], 0, v[98:99]
	s_add_i32 m0, s22, 0x2000
	s_nop 0
	global_load_lds_dwordx4 v[100:101], off
	s_waitcnt vmcnt(6)
	s_barrier
	s_setprio 1
	v_mfma_f32_16x16x32_bf16 v[54:57], v[202:205], v[156:159], v[54:57]
	v_mfma_f32_16x16x32_bf16 v[50:53], v[210:213], v[156:159], v[50:53]
	v_mfma_f32_16x16x32_bf16 v[38:41], v[202:205], v[164:167], v[38:41]
	v_mfma_f32_16x16x32_bf16 v[34:37], v[210:213], v[164:167], v[34:37]
	v_mfma_f32_16x16x32_bf16 v[22:25], v[202:205], v[172:175], v[22:25]
	v_mfma_f32_16x16x32_bf16 v[18:21], v[210:213], v[172:175], v[18:21]
	v_mfma_f32_16x16x32_bf16 v[6:9], v[202:205], v[184:187], v[6:9]
	v_mfma_f32_16x16x32_bf16 v[2:5], v[210:213], v[184:187], v[2:5]
	v_mfma_f32_16x16x32_bf16 v[54:57], v[206:209], v[160:163], v[54:57]
	v_mfma_f32_16x16x32_bf16 v[50:53], v[214:217], v[160:163], v[50:53]
	v_mfma_f32_16x16x32_bf16 v[38:41], v[206:209], v[168:171], v[38:41]
	v_mfma_f32_16x16x32_bf16 v[34:37], v[214:217], v[168:171], v[34:37]
	v_mfma_f32_16x16x32_bf16 v[22:25], v[206:209], v[176:179], v[22:25]
	v_mfma_f32_16x16x32_bf16 v[18:21], v[214:217], v[176:179], v[18:21]
	v_mfma_f32_16x16x32_bf16 v[6:9], v[206:209], v[188:191], v[6:9]
	v_mfma_f32_16x16x32_bf16 v[2:5], v[214:217], v[188:191], v[2:5]
	s_setprio 0
	s_add_i32 s46, s46, 2
	s_add_u32 s18, s18, 0x100
	s_addc_u32 s19, s19, 0
	s_add_u32 s33, s33, 0x100
	s_addc_u32 s45, s45, 0
	s_cmp_gt_u32 s46, 29
	s_barrier
	s_cbranch_scc0 .LBB0_1447
	s_min_i32 s17, s14, 64
	s_ashr_i32 s17, s17, 4
	v_mov_b32_e32 v98, v153
	s_mov_b32 s15, s41
	v_mov_b32_e32 v0, v152
	s_mov_b32 s7, s27
	s_lshl_b32 s9, s14, 8
	s_mul_hi_i32 s19, s17, 0xc000
	s_mul_i32 s17, s17, 0xc000
	s_add_u32 s18, s38, s17
	s_addc_u32 s19, s39, s19
	s_lshl_b32 s16, s16, 8
	s_lshl_b32 s15, s15, 5
	s_add_i32 s15, s15, s16
	v_lshl_add_u32 v146, v98, 2, s15
	v_ashrrev_i32_e32 v147, 31, v146
	v_lshl_add_u64 v[98:99], v[146:147], 2, s[18:19]
	global_load_dwordx4 v[118:121], v[98:99], off
	global_load_dwordx4 v[106:109], v[98:99], off offset:64
	global_load_dwordx4 v[102:105], v[98:99], off offset:512
	s_nop 0
	global_load_dwordx4 v[98:101], v[98:99], off offset:576
	v_readlane_b32 s16, v254, 28
	v_readlane_b32 s17, v254, 29
	s_andn2_b64 vcc, exec, s[16:17]
	s_mov_b64 s[16:17], -1
	s_cbranch_vccnz .LBB0_1451
	s_lshl_b32 s15, s7, 6
	s_add_i32 s15, s15, s9
	v_add_u32_e32 v148, s15, v0
	v_ashrrev_i32_e32 v149, 31, v148
	v_lshlrev_b64 v[148:149], 12, v[148:149]
	v_lshl_add_u64 v[148:149], s[4:5], 0, v[148:149]
	v_lshl_add_u64 v[148:149], v[146:147], 1, v[148:149]
	global_load_dwordx2 v[150:151], v[148:149], off
	global_load_dwordx2 v[206:207], v[148:149], off offset:32
	global_load_dwordx2 v[208:209], v[148:149], off offset:256
	global_load_dwordx2 v[210:211], v[148:149], off offset:288
	s_mov_b32 s15, 0x10000
	s_mov_b64 s[16:17], 0x10000
	s_waitcnt vmcnt(3)
	v_lshlrev_b32_e32 v156, 16, v150
	v_and_b32_e32 v157, 0xffff0000, v150
	v_lshlrev_b32_e32 v150, 16, v151
	v_and_b32_e32 v151, 0xffff0000, v151
	v_pk_fma_f32 v[150:151], v[144:145], v[120:121], v[150:151]
	v_pk_fma_f32 v[156:157], v[142:143], v[118:119], v[156:157]
	s_nop 0
	v_cvt_pk_bf16_f32 v156, v156, v157
	v_cvt_pk_bf16_f32 v157, v150, v151
	s_nop 0
	global_store_dwordx2 v[148:149], v[156:157], off
	s_waitcnt vmcnt(3)
	v_lshlrev_b32_e32 v156, 16, v206
	v_and_b32_e32 v157, 0xffff0000, v206
	v_lshlrev_b32_e32 v150, 16, v207
	v_and_b32_e32 v151, 0xffff0000, v207
	v_pk_fma_f32 v[150:151], v[140:141], v[108:109], v[150:151]
	v_pk_fma_f32 v[156:157], v[138:139], v[106:107], v[156:157]
	s_nop 0
	v_cvt_pk_bf16_f32 v156, v156, v157
	v_cvt_pk_bf16_f32 v157, v150, v151
	s_nop 0
	global_store_dwordx2 v[148:149], v[156:157], off offset:32
	s_waitcnt vmcnt(3)
	v_lshlrev_b32_e32 v156, 16, v208
	v_and_b32_e32 v157, 0xffff0000, v208
	v_lshlrev_b32_e32 v150, 16, v209
	v_and_b32_e32 v151, 0xffff0000, v209
	v_pk_fma_f32 v[150:151], v[136:137], v[104:105], v[150:151]
	v_pk_fma_f32 v[156:157], v[134:135], v[102:103], v[156:157]
	s_nop 0
	v_cvt_pk_bf16_f32 v156, v156, v157
	v_cvt_pk_bf16_f32 v157, v150, v151
	s_nop 0
	global_store_dwordx2 v[148:149], v[156:157], off offset:256
	s_waitcnt vmcnt(3)
; DI unsigned pk2(float a, float b) { f32x2 v = {a, b}; bfv2 r = __builtin_convertvector(v, bfv2); return __builtin_bit_cast(unsigned, r); }
;     DI void operator()(AccRef acc, const Unit& u, int wr, int wc, int fr, int fq) const {
;     ...
;             for (int ai = 0; ai < 2; ++ai)
; #pragma unroll
;                 for (int m = 0; m < 4; ++m) { const size_t off = (size_t)(row0 + wr * 64 + fr + ai * 128 + m * 16) * D + col0;
; #pragma unroll
;                     for (int bj = 0; bj < 2; ++bj)
; #pragma unroll
;                         for (int n = 0; n < 2; ++n) { const size_t o2 = off + bj * 128 + n * 16;
;                             const f32x4 r = bf4(*(const u32x2*)(xb + o2)) + gv[bj][n] * acc[ai][bj][m][n];
;                             u32x2 w; w.x = pk2(r[0], r[1]); w.y = pk2(r[2], r[3]); *(u32x2*)(out + o2) = w; }
;                     asm volatile("" ::: "memory"); }
	v_lshlrev_b32_e32 v156, 16, v210
	v_and_b32_e32 v157, 0xffff0000, v210
	v_lshlrev_b32_e32 v150, 16, v211
	v_and_b32_e32 v151, 0xffff0000, v211
	v_pk_fma_f32 v[150:151], v[132:133], v[100:101], v[150:151]
	v_pk_fma_f32 v[156:157], v[130:131], v[98:99], v[156:157]
	s_nop 0
	v_cvt_pk_bf16_f32 v156, v156, v157
	v_cvt_pk_bf16_f32 v157, v150, v151
	global_store_dwordx2 v[148:149], v[156:157], off offset:288
	v_add_co_u32_e32 v156, vcc, s15, v148
	v_lshl_add_u64 v[150:151], v[148:149], 0, s[16:17]
	s_nop 0
	v_addc_co_u32_e32 v157, vcc, 0, v149, vcc
	global_load_dwordx2 v[158:159], v[156:157], off
	global_load_dwordx2 v[206:207], v[150:151], off offset:32
	global_load_dwordx2 v[208:209], v[150:151], off offset:256
	global_load_dwordx2 v[210:211], v[150:151], off offset:288
	s_mov_b32 s15, 0x20000
	s_mov_b64 s[16:17], 0x20000
	s_waitcnt vmcnt(3)
	v_lshlrev_b32_e32 v160, 16, v158
	v_and_b32_e32 v161, 0xffff0000, v158
	v_lshlrev_b32_e32 v158, 16, v159
	v_and_b32_e32 v159, 0xffff0000, v159
	v_pk_fma_f32 v[158:159], v[128:129], v[120:121], v[158:159]
	v_pk_fma_f32 v[160:161], v[126:127], v[118:119], v[160:161]
	s_nop 0
	v_cvt_pk_bf16_f32 v160, v160, v161
	v_cvt_pk_bf16_f32 v161, v158, v159
	global_store_dwordx2 v[156:157], v[160:161], off
	s_waitcnt vmcnt(3)
	v_lshlrev_b32_e32 v158, 16, v206
	v_and_b32_e32 v159, 0xffff0000, v206
	v_lshlrev_b32_e32 v156, 16, v207
	v_and_b32_e32 v157, 0xffff0000, v207
	v_pk_fma_f32 v[156:157], v[124:125], v[108:109], v[156:157]
	v_pk_fma_f32 v[158:159], v[122:123], v[106:107], v[158:159]
	s_nop 0
	v_cvt_pk_bf16_f32 v158, v158, v159
	v_cvt_pk_bf16_f32 v159, v156, v157
	s_nop 0
	global_store_dwordx2 v[150:151], v[158:159], off offset:32
	s_waitcnt vmcnt(3)
	v_lshlrev_b32_e32 v158, 16, v208
	v_and_b32_e32 v159, 0xffff0000, v208
	v_lshlrev_b32_e32 v156, 16, v209
	v_and_b32_e32 v157, 0xffff0000, v209
	v_pk_fma_f32 v[156:157], v[116:117], v[104:105], v[156:157]
	v_pk_fma_f32 v[158:159], v[114:115], v[102:103], v[158:159]
	s_nop 0
	v_cvt_pk_bf16_f32 v158, v158, v159
	v_cvt_pk_bf16_f32 v159, v156, v157
	s_nop 0
	global_store_dwordx2 v[150:151], v[158:159], off offset:256
	s_waitcnt vmcnt(3)
	v_lshlrev_b32_e32 v158, 16, v210
	v_and_b32_e32 v159, 0xffff0000, v210
	v_lshlrev_b32_e32 v156, 16, v211
	v_and_b32_e32 v157, 0xffff0000, v211
	v_pk_fma_f32 v[156:157], v[112:113], v[100:101], v[156:157]
	v_pk_fma_f32 v[158:159], v[110:111], v[98:99], v[158:159]
	s_nop 0
	v_cvt_pk_bf16_f32 v158, v158, v159
	v_cvt_pk_bf16_f32 v159, v156, v157
	global_store_dwordx2 v[150:151], v[158:159], off offset:288
	v_add_co_u32_e32 v156, vcc, s15, v148
	v_lshl_add_u64 v[150:151], v[148:149], 0, s[16:17]
	s_nop 0
	v_addc_co_u32_e32 v157, vcc, 0, v149, vcc
	global_load_dwordx2 v[158:159], v[156:157], off
	global_load_dwordx2 v[206:207], v[150:151], off offset:32
	global_load_dwordx2 v[208:209], v[150:151], off offset:256
	global_load_dwordx2 v[210:211], v[150:151], off offset:288
	s_mov_b32 s15, 0x30000
	s_mov_b64 s[16:17], 0x30000
	s_waitcnt vmcnt(3)
	v_lshlrev_b32_e32 v160, 16, v158
	v_and_b32_e32 v161, 0xffff0000, v158
	v_lshlrev_b32_e32 v158, 16, v159
	v_and_b32_e32 v159, 0xffff0000, v159
	v_pk_fma_f32 v[158:159], v[96:97], v[120:121], v[158:159]
	v_pk_fma_f32 v[160:161], v[94:95], v[118:119], v[160:161]
	s_nop 0
	v_cvt_pk_bf16_f32 v160, v160, v161
	v_cvt_pk_bf16_f32 v161, v158, v159
	global_store_dwordx2 v[156:157], v[160:161], off
	s_waitcnt vmcnt(3)
	v_lshlrev_b32_e32 v158, 16, v206
	v_and_b32_e32 v159, 0xffff0000, v206
	v_lshlrev_b32_e32 v156, 16, v207
	v_and_b32_e32 v157, 0xffff0000, v207
	v_pk_fma_f32 v[156:157], v[92:93], v[108:109], v[156:157]
	v_pk_fma_f32 v[158:159], v[90:91], v[106:107], v[158:159]
	s_nop 0
	v_cvt_pk_bf16_f32 v158, v158, v159
	v_cvt_pk_bf16_f32 v159, v156, v157
	s_nop 0
	global_store_dwordx2 v[150:151], v[158:159], off offset:32
	s_waitcnt vmcnt(3)
	v_lshlrev_b32_e32 v158, 16, v208
	v_and_b32_e32 v159, 0xffff0000, v208
	v_lshlrev_b32_e32 v156, 16, v209
	v_and_b32_e32 v157, 0xffff0000, v209
	v_pk_fma_f32 v[156:157], v[88:89], v[104:105], v[156:157]
	v_pk_fma_f32 v[158:159], v[86:87], v[102:103], v[158:159]
	s_nop 0
	v_cvt_pk_bf16_f32 v158, v158, v159
	v_cvt_pk_bf16_f32 v159, v156, v157
	s_nop 0
	global_store_dwordx2 v[150:151], v[158:159], off offset:256
	s_waitcnt vmcnt(3)
	v_lshlrev_b32_e32 v158, 16, v210
	v_and_b32_e32 v159, 0xffff0000, v210
	v_lshlrev_b32_e32 v156, 16, v211
	v_and_b32_e32 v157, 0xffff0000, v211
	v_pk_fma_f32 v[156:157], v[84:85], v[100:101], v[156:157]
	v_pk_fma_f32 v[158:159], v[82:83], v[98:99], v[158:159]
	s_nop 0
	v_cvt_pk_bf16_f32 v158, v158, v159
	v_cvt_pk_bf16_f32 v159, v156, v157
	global_store_dwordx2 v[150:151], v[158:159], off offset:288
	v_add_co_u32_e32 v156, vcc, s15, v148
	v_lshl_add_u64 v[150:151], v[148:149], 0, s[16:17]
	s_nop 0
	v_addc_co_u32_e32 v157, vcc, 0, v149, vcc
	global_load_dwordx2 v[158:159], v[156:157], off
	global_load_dwordx2 v[206:207], v[150:151], off offset:32
	global_load_dwordx2 v[208:209], v[150:151], off offset:256
	global_load_dwordx2 v[210:211], v[150:151], off offset:288
	s_mov_b32 s15, 0x80000
	s_mov_b64 s[16:17], 0x80000
	s_waitcnt vmcnt(3)
	v_lshlrev_b32_e32 v160, 16, v158
	v_and_b32_e32 v161, 0xffff0000, v158
	v_lshlrev_b32_e32 v158, 16, v159
	v_and_b32_e32 v159, 0xffff0000, v159
	v_pk_fma_f32 v[158:159], v[80:81], v[120:121], v[158:159]
	v_pk_fma_f32 v[160:161], v[78:79], v[118:119], v[160:161]
	s_nop 0
	v_cvt_pk_bf16_f32 v160, v160, v161
	v_cvt_pk_bf16_f32 v161, v158, v159
	global_store_dwordx2 v[156:157], v[160:161], off
	s_waitcnt vmcnt(3)
; DI unsigned pk2(float a, float b) { f32x2 v = {a, b}; bfv2 r = __builtin_convertvector(v, bfv2); return __builtin_bit_cast(unsigned, r); }
;     DI void operator()(AccRef acc, const Unit& u, int wr, int wc, int fr, int fq) const {
;     ...
;             for (int ai = 0; ai < 2; ++ai)
; #pragma unroll
;                 for (int m = 0; m < 4; ++m) { const size_t off = (size_t)(row0 + wr * 64 + fr + ai * 128 + m * 16) * D + col0;
; #pragma unroll
;                     for (int bj = 0; bj < 2; ++bj)
; #pragma unroll
;                         for (int n = 0; n < 2; ++n) { const size_t o2 = off + bj * 128 + n * 16;
;                             const f32x4 r = bf4(*(const u32x2*)(xb + o2)) + gv[bj][n] * acc[ai][bj][m][n];
;                             u32x2 w; w.x = pk2(r[0], r[1]); w.y = pk2(r[2], r[3]); *(u32x2*)(out + o2) = w; }
;                     asm volatile("" ::: "memory"); }
	v_lshlrev_b32_e32 v158, 16, v206
	v_and_b32_e32 v159, 0xffff0000, v206
	v_lshlrev_b32_e32 v156, 16, v207
	v_and_b32_e32 v157, 0xffff0000, v207
	v_pk_fma_f32 v[156:157], v[76:77], v[108:109], v[156:157]
	v_pk_fma_f32 v[158:159], v[74:75], v[106:107], v[158:159]
	s_nop 0
	v_cvt_pk_bf16_f32 v158, v158, v159
	v_cvt_pk_bf16_f32 v159, v156, v157
	s_nop 0
	global_store_dwordx2 v[150:151], v[158:159], off offset:32
	s_waitcnt vmcnt(3)
	v_lshlrev_b32_e32 v158, 16, v208
	v_and_b32_e32 v159, 0xffff0000, v208
	v_lshlrev_b32_e32 v156, 16, v209
	v_and_b32_e32 v157, 0xffff0000, v209
	v_pk_fma_f32 v[156:157], v[72:73], v[104:105], v[156:157]
	v_pk_fma_f32 v[158:159], v[70:71], v[102:103], v[158:159]
	s_nop 0
	v_cvt_pk_bf16_f32 v158, v158, v159
	v_cvt_pk_bf16_f32 v159, v156, v157
	s_nop 0
	global_store_dwordx2 v[150:151], v[158:159], off offset:256
	s_waitcnt vmcnt(3)
	v_lshlrev_b32_e32 v158, 16, v210
	v_and_b32_e32 v159, 0xffff0000, v210
	v_lshlrev_b32_e32 v156, 16, v211
	v_and_b32_e32 v157, 0xffff0000, v211
	v_pk_fma_f32 v[156:157], v[68:69], v[100:101], v[156:157]
	v_pk_fma_f32 v[158:159], v[66:67], v[98:99], v[158:159]
	s_nop 0
	v_cvt_pk_bf16_f32 v158, v158, v159
	v_cvt_pk_bf16_f32 v159, v156, v157
	global_store_dwordx2 v[150:151], v[158:159], off offset:288
	v_add_co_u32_e32 v156, vcc, s15, v148
	v_lshl_add_u64 v[150:151], v[148:149], 0, s[16:17]
	s_nop 0
	v_addc_co_u32_e32 v157, vcc, 0, v149, vcc
	global_load_dwordx2 v[158:159], v[156:157], off
	global_load_dwordx2 v[206:207], v[150:151], off offset:32
	global_load_dwordx2 v[208:209], v[150:151], off offset:256
	global_load_dwordx2 v[210:211], v[150:151], off offset:288
	s_mov_b32 s15, 0x90000
	s_mov_b64 s[16:17], 0x90000
	s_waitcnt vmcnt(3)
	v_lshlrev_b32_e32 v160, 16, v158
	v_and_b32_e32 v161, 0xffff0000, v158
	v_lshlrev_b32_e32 v158, 16, v159
	v_and_b32_e32 v159, 0xffff0000, v159
	v_pk_fma_f32 v[158:159], v[64:65], v[120:121], v[158:159]
	v_pk_fma_f32 v[160:161], v[62:63], v[118:119], v[160:161]
	s_nop 0
	v_cvt_pk_bf16_f32 v160, v160, v161
	v_cvt_pk_bf16_f32 v161, v158, v159
	global_store_dwordx2 v[156:157], v[160:161], off
	s_waitcnt vmcnt(3)
	v_lshlrev_b32_e32 v158, 16, v206
	v_and_b32_e32 v159, 0xffff0000, v206
	v_lshlrev_b32_e32 v156, 16, v207
	v_and_b32_e32 v157, 0xffff0000, v207
	v_pk_fma_f32 v[156:157], v[60:61], v[108:109], v[156:157]
	v_pk_fma_f32 v[158:159], v[58:59], v[106:107], v[158:159]
	s_nop 0
	v_cvt_pk_bf16_f32 v158, v158, v159
	v_cvt_pk_bf16_f32 v159, v156, v157
	s_nop 0
	global_store_dwordx2 v[150:151], v[158:159], off offset:32
	s_waitcnt vmcnt(3)
	v_lshlrev_b32_e32 v158, 16, v208
	v_and_b32_e32 v159, 0xffff0000, v208
	v_lshlrev_b32_e32 v156, 16, v209
	v_and_b32_e32 v157, 0xffff0000, v209
	v_pk_fma_f32 v[156:157], v[56:57], v[104:105], v[156:157]
	v_pk_fma_f32 v[158:159], v[54:55], v[102:103], v[158:159]
	s_nop 0
	v_cvt_pk_bf16_f32 v158, v158, v159
	v_cvt_pk_bf16_f32 v159, v156, v157
	s_nop 0
	global_store_dwordx2 v[150:151], v[158:159], off offset:256
	s_waitcnt vmcnt(3)
	v_lshlrev_b32_e32 v158, 16, v210
	v_and_b32_e32 v159, 0xffff0000, v210
	v_lshlrev_b32_e32 v156, 16, v211
	v_and_b32_e32 v157, 0xffff0000, v211
	v_pk_fma_f32 v[156:157], v[52:53], v[100:101], v[156:157]
	v_pk_fma_f32 v[158:159], v[50:51], v[98:99], v[158:159]
	s_nop 0
	v_cvt_pk_bf16_f32 v158, v158, v159
	v_cvt_pk_bf16_f32 v159, v156, v157
	global_store_dwordx2 v[150:151], v[158:159], off offset:288
	v_add_co_u32_e32 v156, vcc, s15, v148
	v_lshl_add_u64 v[150:151], v[148:149], 0, s[16:17]
	s_nop 0
	v_addc_co_u32_e32 v157, vcc, 0, v149, vcc
	global_load_dwordx2 v[158:159], v[156:157], off
	global_load_dwordx2 v[206:207], v[150:151], off offset:32
	global_load_dwordx2 v[208:209], v[150:151], off offset:256
	global_load_dwordx2 v[210:211], v[150:151], off offset:288
	s_mov_b32 s15, 0xa0000
	s_mov_b64 s[16:17], 0xa0000
	s_waitcnt vmcnt(3)
	v_lshlrev_b32_e32 v160, 16, v158
	v_and_b32_e32 v161, 0xffff0000, v158
	v_lshlrev_b32_e32 v158, 16, v159
	v_and_b32_e32 v159, 0xffff0000, v159
	v_pk_fma_f32 v[158:159], v[48:49], v[120:121], v[158:159]
	v_pk_fma_f32 v[160:161], v[46:47], v[118:119], v[160:161]
	s_nop 0
	v_cvt_pk_bf16_f32 v160, v160, v161
	v_cvt_pk_bf16_f32 v161, v158, v159
	global_store_dwordx2 v[156:157], v[160:161], off
	s_waitcnt vmcnt(3)
	v_lshlrev_b32_e32 v158, 16, v206
	v_and_b32_e32 v159, 0xffff0000, v206
	v_lshlrev_b32_e32 v156, 16, v207
	v_and_b32_e32 v157, 0xffff0000, v207
	v_pk_fma_f32 v[156:157], v[44:45], v[108:109], v[156:157]
	v_pk_fma_f32 v[158:159], v[42:43], v[106:107], v[158:159]
	s_nop 0
	v_cvt_pk_bf16_f32 v158, v158, v159
	v_cvt_pk_bf16_f32 v159, v156, v157
	s_nop 0
	global_store_dwordx2 v[150:151], v[158:159], off offset:32
	s_waitcnt vmcnt(3)
; DI unsigned pk2(float a, float b) { f32x2 v = {a, b}; bfv2 r = __builtin_convertvector(v, bfv2); return __builtin_bit_cast(unsigned, r); }
;     DI void operator()(AccRef acc, const Unit& u, int wr, int wc, int fr, int fq) const {
;     ...
;             for (int ai = 0; ai < 2; ++ai)
; #pragma unroll
;                 for (int m = 0; m < 4; ++m) { const size_t off = (size_t)(row0 + wr * 64 + fr + ai * 128 + m * 16) * D + col0;
; #pragma unroll
;                     for (int bj = 0; bj < 2; ++bj)
; #pragma unroll
;                         for (int n = 0; n < 2; ++n) { const size_t o2 = off + bj * 128 + n * 16;
;                             const f32x4 r = bf4(*(const u32x2*)(xb + o2)) + gv[bj][n] * acc[ai][bj][m][n];
;                             u32x2 w; w.x = pk2(r[0], r[1]); w.y = pk2(r[2], r[3]); *(u32x2*)(out + o2) = w; }
;                     asm volatile("" ::: "memory"); }
	v_lshlrev_b32_e32 v158, 16, v208
	v_and_b32_e32 v159, 0xffff0000, v208
	v_lshlrev_b32_e32 v156, 16, v209
	v_and_b32_e32 v157, 0xffff0000, v209
	v_pk_fma_f32 v[156:157], v[40:41], v[104:105], v[156:157]
	v_pk_fma_f32 v[158:159], v[38:39], v[102:103], v[158:159]
	s_nop 0
	v_cvt_pk_bf16_f32 v158, v158, v159
	v_cvt_pk_bf16_f32 v159, v156, v157
	s_nop 0
	global_store_dwordx2 v[150:151], v[158:159], off offset:256
	s_waitcnt vmcnt(3)
	v_lshlrev_b32_e32 v158, 16, v210
	v_and_b32_e32 v159, 0xffff0000, v210
	v_lshlrev_b32_e32 v156, 16, v211
	v_and_b32_e32 v157, 0xffff0000, v211
	v_pk_fma_f32 v[156:157], v[36:37], v[100:101], v[156:157]
	v_pk_fma_f32 v[158:159], v[34:35], v[98:99], v[158:159]
	s_nop 0
	v_cvt_pk_bf16_f32 v158, v158, v159
	v_cvt_pk_bf16_f32 v159, v156, v157
	global_store_dwordx2 v[150:151], v[158:159], off offset:288
	v_add_co_u32_e32 v156, vcc, s15, v148
	v_lshl_add_u64 v[150:151], v[148:149], 0, s[16:17]
	s_nop 0
	v_addc_co_u32_e32 v157, vcc, 0, v149, vcc
	global_load_dwordx2 v[158:159], v[156:157], off
	global_load_dwordx2 v[206:207], v[150:151], off offset:32
	global_load_dwordx2 v[208:209], v[150:151], off offset:256
	global_load_dwordx2 v[210:211], v[150:151], off offset:288
	s_mov_b64 s[16:17], 0xb0000
	s_mov_b32 s15, 0xb0000
	s_waitcnt vmcnt(3)
	v_lshlrev_b32_e32 v160, 16, v158
	v_and_b32_e32 v161, 0xffff0000, v158
	v_lshlrev_b32_e32 v158, 16, v159
	v_and_b32_e32 v159, 0xffff0000, v159
	v_pk_fma_f32 v[158:159], v[32:33], v[120:121], v[158:159]
	v_pk_fma_f32 v[160:161], v[30:31], v[118:119], v[160:161]
	s_nop 0
	v_cvt_pk_bf16_f32 v160, v160, v161
	v_cvt_pk_bf16_f32 v161, v158, v159
	global_store_dwordx2 v[156:157], v[160:161], off
	s_waitcnt vmcnt(3)
	v_lshlrev_b32_e32 v158, 16, v206
	v_and_b32_e32 v159, 0xffff0000, v206
	v_lshlrev_b32_e32 v156, 16, v207
	v_and_b32_e32 v157, 0xffff0000, v207
	v_pk_fma_f32 v[156:157], v[28:29], v[108:109], v[156:157]
	v_pk_fma_f32 v[158:159], v[26:27], v[106:107], v[158:159]
	s_nop 0
	v_cvt_pk_bf16_f32 v158, v158, v159
	v_cvt_pk_bf16_f32 v159, v156, v157
	s_nop 0
	global_store_dwordx2 v[150:151], v[158:159], off offset:32
	s_waitcnt vmcnt(3)
	v_lshlrev_b32_e32 v158, 16, v208
	v_and_b32_e32 v159, 0xffff0000, v208
	v_lshlrev_b32_e32 v156, 16, v209
	v_and_b32_e32 v157, 0xffff0000, v209
	v_pk_fma_f32 v[156:157], v[24:25], v[104:105], v[156:157]
	v_pk_fma_f32 v[158:159], v[22:23], v[102:103], v[158:159]
	s_nop 0
	v_cvt_pk_bf16_f32 v158, v158, v159
	v_cvt_pk_bf16_f32 v159, v156, v157
	s_nop 0
	global_store_dwordx2 v[150:151], v[158:159], off offset:256
	s_waitcnt vmcnt(3)
	v_lshlrev_b32_e32 v158, 16, v210
	v_and_b32_e32 v159, 0xffff0000, v210
	v_lshlrev_b32_e32 v156, 16, v211
	v_and_b32_e32 v157, 0xffff0000, v211
	v_pk_fma_f32 v[156:157], v[20:21], v[100:101], v[156:157]
	v_pk_fma_f32 v[158:159], v[18:19], v[98:99], v[158:159]
	s_nop 0
	v_cvt_pk_bf16_f32 v158, v158, v159
	v_cvt_pk_bf16_f32 v159, v156, v157
	global_store_dwordx2 v[150:151], v[158:159], off offset:288
	v_lshl_add_u64 v[150:151], v[148:149], 0, s[16:17]
	v_add_co_u32_e32 v148, vcc, s15, v148
	s_nop 1
	v_addc_co_u32_e32 v149, vcc, 0, v149, vcc
	global_load_dwordx2 v[156:157], v[148:149], off
	global_load_dwordx2 v[206:207], v[150:151], off offset:32
	global_load_dwordx2 v[208:209], v[150:151], off offset:256
	global_load_dwordx2 v[210:211], v[150:151], off offset:288
	s_waitcnt vmcnt(3)
	v_lshlrev_b32_e32 v158, 16, v156
	v_and_b32_e32 v159, 0xffff0000, v156
	v_lshlrev_b32_e32 v156, 16, v157
	v_and_b32_e32 v157, 0xffff0000, v157
	v_pk_fma_f32 v[156:157], v[16:17], v[120:121], v[156:157]
	v_pk_fma_f32 v[158:159], v[14:15], v[118:119], v[158:159]
	s_nop 0
	v_cvt_pk_bf16_f32 v158, v158, v159
	v_cvt_pk_bf16_f32 v159, v156, v157
	global_store_dwordx2 v[148:149], v[158:159], off
	s_waitcnt vmcnt(3)
	v_lshlrev_b32_e32 v156, 16, v206
	v_and_b32_e32 v157, 0xffff0000, v206
	v_lshlrev_b32_e32 v148, 16, v207
	v_and_b32_e32 v149, 0xffff0000, v207
	v_pk_fma_f32 v[148:149], v[12:13], v[108:109], v[148:149]
	v_pk_fma_f32 v[156:157], v[10:11], v[106:107], v[156:157]
	s_nop 0
	v_cvt_pk_bf16_f32 v156, v156, v157
	v_cvt_pk_bf16_f32 v157, v148, v149
	s_nop 0
	global_store_dwordx2 v[150:151], v[156:157], off offset:32
	s_waitcnt vmcnt(3)
	v_lshlrev_b32_e32 v156, 16, v208
	v_and_b32_e32 v157, 0xffff0000, v208
	v_lshlrev_b32_e32 v148, 16, v209
	v_and_b32_e32 v149, 0xffff0000, v209
	v_pk_fma_f32 v[148:149], v[8:9], v[104:105], v[148:149]
	v_pk_fma_f32 v[156:157], v[6:7], v[102:103], v[156:157]
	s_nop 0
	v_cvt_pk_bf16_f32 v156, v156, v157
	v_cvt_pk_bf16_f32 v157, v148, v149
	s_nop 0
	global_store_dwordx2 v[150:151], v[156:157], off offset:256
	s_waitcnt vmcnt(3)
	v_lshlrev_b32_e32 v156, 16, v210
	v_and_b32_e32 v157, 0xffff0000, v210
	v_lshlrev_b32_e32 v148, 16, v211
	v_and_b32_e32 v149, 0xffff0000, v211
	v_pk_fma_f32 v[148:149], v[4:5], v[100:101], v[148:149]
	v_pk_fma_f32 v[156:157], v[2:3], v[98:99], v[156:157]
	s_nop 0
	v_cvt_pk_bf16_f32 v156, v156, v157
	v_cvt_pk_bf16_f32 v157, v148, v149
	global_store_dwordx2 v[150:151], v[156:157], off offset:288
	s_cbranch_execz .LBB0_1452

; DI unsigned pk2(float a, float b) { f32x2 v = {a, b}; bfv2 r = __builtin_convertvector(v, bfv2); return __builtin_bit_cast(unsigned, r); }
;     DI void operator()(AccRef acc, const Unit& u, int wr, int wc, int fr, int fq) const {
;     ...
;         } else {
; #pragma unroll
;             for (int ai = 0; ai < 2; ++ai)
; #pragma unroll
;                 for (int m = 0; m < 4; ++m) { const size_t off = (size_t)(row0 + wr * 64 + fr + ai * 128 + m * 16) * D + col0;
; #pragma unroll
;                     for (int bj = 0; bj < 2; ++bj)
; #pragma unroll
;                         for (int n = 0; n < 2; ++n) { const size_t o2 = off + bj * 128 + n * 16;
;                             const f32x4 r = *(const f32x4*)(src + o2) + gv[bj][n] * acc[ai][bj][m][n];
;                             u32x2 w; w.x = pk2(r[0], r[1]); w.y = pk2(r[2], r[3]); *(u32x2*)(out + o2) = w; }
;                     asm volatile("" ::: "memory"); }
.LBB0_1452:
	s_cmp_lt_i32 s14, 64
	s_mov_b64 s[14:15], s[56:57]
	v_readlane_b32 s48, v254, 39
	v_readlane_b32 s56, v254, 47
	v_readlane_b32 s57, v254, 48
	v_readlane_b32 s49, v254, 40
	s_mov_b64 s[56:57], s[14:15]
	v_readlane_b32 s14, v255, 5
	s_cselect_b32 s15, s49, s14
	v_readlane_b32 s14, v255, 4
	s_cselect_b32 s14, s48, s14
	s_lshl_b32 s7, s7, 6
	s_add_i32 s7, s7, s9
	v_add_u32_e32 v148, s7, v0
	v_ashrrev_i32_e32 v149, 31, v148
	v_lshlrev_b64 v[148:149], 11, v[148:149]
	v_lshl_add_u64 v[146:147], v[148:149], 0, v[146:147]
	v_lshl_add_u64 v[156:157], v[146:147], 2, s[14:15]
	global_load_dwordx4 v[148:151], v[156:157], off
	global_load_dwordx4 v[206:209], v[156:157], off offset:64
	global_load_dwordx4 v[210:213], v[156:157], off offset:512
	global_load_dwordx4 v[214:217], v[156:157], off offset:576
	s_mov_b64 s[16:17], 0x8000
	v_readlane_b32 s50, v254, 41
	v_readlane_b32 s51, v254, 42
	v_readlane_b32 s52, v254, 43
	v_readlane_b32 s53, v254, 44
	v_readlane_b32 s54, v254, 45
	v_readlane_b32 s55, v254, 46
	v_readlane_b32 s58, v254, 49
	v_readlane_b32 s59, v254, 50
	v_readlane_b32 s60, v254, 51
	v_readlane_b32 s61, v254, 52
	v_readlane_b32 s62, v254, 53
	v_readlane_b32 s63, v254, 54
	s_waitcnt vmcnt(3)
	v_pk_fma_f32 v[144:145], v[144:145], v[120:121], v[150:151]
	v_pk_fma_f32 v[142:143], v[142:143], v[118:119], v[148:149]
	v_lshl_add_u64 v[148:149], v[146:147], 1, s[4:5]
	v_cvt_pk_bf16_f32 v142, v142, v143
	v_cvt_pk_bf16_f32 v143, v144, v145
	global_store_dwordx2 v[148:149], v[142:143], off
	s_waitcnt vmcnt(3)
	v_pk_fma_f32 v[140:141], v[140:141], v[108:109], v[208:209]
	v_pk_fma_f32 v[138:139], v[138:139], v[106:107], v[206:207]
	s_nop 0
	v_cvt_pk_bf16_f32 v138, v138, v139
	v_cvt_pk_bf16_f32 v139, v140, v141
	global_store_dwordx2 v[148:149], v[138:139], off offset:32
	s_waitcnt vmcnt(3)
	v_pk_fma_f32 v[136:137], v[136:137], v[104:105], v[212:213]
	v_pk_fma_f32 v[134:135], v[134:135], v[102:103], v[210:211]
	s_nop 0
	v_cvt_pk_bf16_f32 v134, v134, v135
	v_cvt_pk_bf16_f32 v135, v136, v137
	global_store_dwordx2 v[148:149], v[134:135], off offset:256
	s_waitcnt vmcnt(3)
	v_pk_fma_f32 v[132:133], v[132:133], v[100:101], v[216:217]
	v_pk_fma_f32 v[130:131], v[130:131], v[98:99], v[214:215]
	v_lshl_add_u64 v[134:135], v[146:147], 0, s[16:17]
	v_cvt_pk_bf16_f32 v130, v130, v131
	v_cvt_pk_bf16_f32 v131, v132, v133
	global_store_dwordx2 v[148:149], v[130:131], off offset:288
	v_lshl_add_u64 v[136:137], v[134:135], 2, s[14:15]
	global_load_dwordx4 v[130:133], v[136:137], off
	global_load_dwordx4 v[206:209], v[136:137], off offset:64
	global_load_dwordx4 v[210:213], v[136:137], off offset:512
	global_load_dwordx4 v[214:217], v[136:137], off offset:576
	s_mov_b64 s[16:17], 0x10000
	s_waitcnt vmcnt(3)
	v_pk_fma_f32 v[128:129], v[128:129], v[120:121], v[132:133]
	v_pk_fma_f32 v[126:127], v[126:127], v[118:119], v[130:131]
	v_lshl_add_u64 v[130:131], v[134:135], 1, s[4:5]
	v_cvt_pk_bf16_f32 v126, v126, v127
	v_cvt_pk_bf16_f32 v127, v128, v129
	global_store_dwordx2 v[130:131], v[126:127], off
	s_waitcnt vmcnt(3)
	v_pk_fma_f32 v[124:125], v[124:125], v[108:109], v[208:209]
	v_pk_fma_f32 v[122:123], v[122:123], v[106:107], v[206:207]
	s_nop 0
	v_cvt_pk_bf16_f32 v122, v122, v123
	v_cvt_pk_bf16_f32 v123, v124, v125
	global_store_dwordx2 v[130:131], v[122:123], off offset:32
	s_waitcnt vmcnt(3)
	v_pk_fma_f32 v[116:117], v[116:117], v[104:105], v[212:213]
	v_pk_fma_f32 v[114:115], v[114:115], v[102:103], v[210:211]
	s_nop 0
	v_cvt_pk_bf16_f32 v114, v114, v115
	v_cvt_pk_bf16_f32 v115, v116, v117
	global_store_dwordx2 v[130:131], v[114:115], off offset:256
	s_waitcnt vmcnt(3)
	v_pk_fma_f32 v[112:113], v[112:113], v[100:101], v[216:217]
	v_pk_fma_f32 v[110:111], v[110:111], v[98:99], v[214:215]
	v_lshl_add_u64 v[114:115], v[146:147], 0, s[16:17]
	v_cvt_pk_bf16_f32 v110, v110, v111
	v_cvt_pk_bf16_f32 v111, v112, v113
	global_store_dwordx2 v[130:131], v[110:111], off offset:288
	v_lshl_add_u64 v[116:117], v[114:115], 2, s[14:15]
	global_load_dwordx4 v[110:113], v[116:117], off
	global_load_dwordx4 v[206:209], v[116:117], off offset:64
	global_load_dwordx4 v[210:213], v[116:117], off offset:512
	global_load_dwordx4 v[214:217], v[116:117], off offset:576
	s_mov_b64 s[16:17], 0x18000
	s_waitcnt vmcnt(3)
	v_pk_fma_f32 v[96:97], v[96:97], v[120:121], v[112:113]
	v_pk_fma_f32 v[94:95], v[94:95], v[118:119], v[110:111]
	v_lshl_add_u64 v[110:111], v[114:115], 1, s[4:5]
	v_cvt_pk_bf16_f32 v94, v94, v95
	v_cvt_pk_bf16_f32 v95, v96, v97
	global_store_dwordx2 v[110:111], v[94:95], off
	s_waitcnt vmcnt(3)
	v_pk_fma_f32 v[92:93], v[92:93], v[108:109], v[208:209]
	v_pk_fma_f32 v[90:91], v[90:91], v[106:107], v[206:207]
	s_nop 0
	v_cvt_pk_bf16_f32 v90, v90, v91
	v_cvt_pk_bf16_f32 v91, v92, v93
	global_store_dwordx2 v[110:111], v[90:91], off offset:32
	s_waitcnt vmcnt(3)
	v_pk_fma_f32 v[88:89], v[88:89], v[104:105], v[212:213]
	v_pk_fma_f32 v[86:87], v[86:87], v[102:103], v[210:211]
	s_nop 0
	v_cvt_pk_bf16_f32 v86, v86, v87
	v_cvt_pk_bf16_f32 v87, v88, v89
	global_store_dwordx2 v[110:111], v[86:87], off offset:256
	s_waitcnt vmcnt(3)
	v_pk_fma_f32 v[84:85], v[84:85], v[100:101], v[216:217]
	v_pk_fma_f32 v[82:83], v[82:83], v[98:99], v[214:215]
	v_lshl_add_u64 v[86:87], v[146:147], 0, s[16:17]
	v_cvt_pk_bf16_f32 v82, v82, v83
	v_cvt_pk_bf16_f32 v83, v84, v85
	global_store_dwordx2 v[110:111], v[82:83], off offset:288
	v_lshl_add_u64 v[88:89], v[86:87], 2, s[14:15]
	global_load_dwordx4 v[82:85], v[88:89], off
	global_load_dwordx4 v[206:209], v[88:89], off offset:64
	global_load_dwordx4 v[210:213], v[88:89], off offset:512
	global_load_dwordx4 v[214:217], v[88:89], off offset:576
	s_mov_b64 s[16:17], 0x40000
	s_waitcnt vmcnt(3)
; DI unsigned pk2(float a, float b) { f32x2 v = {a, b}; bfv2 r = __builtin_convertvector(v, bfv2); return __builtin_bit_cast(unsigned, r); }
;     DI void operator()(AccRef acc, const Unit& u, int wr, int wc, int fr, int fq) const {
;     ...
; #pragma unroll
;             for (int ai = 0; ai < 2; ++ai)
; #pragma unroll
;                 for (int m = 0; m < 4; ++m) { const size_t off = (size_t)(row0 + wr * 64 + fr + ai * 128 + m * 16) * D + col0;
; #pragma unroll
;                     for (int bj = 0; bj < 2; ++bj)
; #pragma unroll
;                         for (int n = 0; n < 2; ++n) { const size_t o2 = off + bj * 128 + n * 16;
;                             const f32x4 r = *(const f32x4*)(src + o2) + gv[bj][n] * acc[ai][bj][m][n];
;                             u32x2 w; w.x = pk2(r[0], r[1]); w.y = pk2(r[2], r[3]); *(u32x2*)(out + o2) = w; }
;                     asm volatile("" ::: "memory"); }
	v_pk_fma_f32 v[80:81], v[80:81], v[120:121], v[84:85]
	v_pk_fma_f32 v[78:79], v[78:79], v[118:119], v[82:83]
	v_lshl_add_u64 v[82:83], v[86:87], 1, s[4:5]
	v_cvt_pk_bf16_f32 v78, v78, v79
	v_cvt_pk_bf16_f32 v79, v80, v81
	global_store_dwordx2 v[82:83], v[78:79], off
	s_waitcnt vmcnt(3)
	v_pk_fma_f32 v[76:77], v[76:77], v[108:109], v[208:209]
	v_pk_fma_f32 v[74:75], v[74:75], v[106:107], v[206:207]
	s_nop 0
	v_cvt_pk_bf16_f32 v74, v74, v75
	v_cvt_pk_bf16_f32 v75, v76, v77
	global_store_dwordx2 v[82:83], v[74:75], off offset:32
	s_waitcnt vmcnt(3)
	v_pk_fma_f32 v[72:73], v[72:73], v[104:105], v[212:213]
	v_pk_fma_f32 v[70:71], v[70:71], v[102:103], v[210:211]
	s_nop 0
	v_cvt_pk_bf16_f32 v70, v70, v71
	v_cvt_pk_bf16_f32 v71, v72, v73
	global_store_dwordx2 v[82:83], v[70:71], off offset:256
	s_waitcnt vmcnt(3)
	v_pk_fma_f32 v[68:69], v[68:69], v[100:101], v[216:217]
	v_pk_fma_f32 v[66:67], v[66:67], v[98:99], v[214:215]
	v_lshl_add_u64 v[70:71], v[146:147], 0, s[16:17]
	v_cvt_pk_bf16_f32 v66, v66, v67
	v_cvt_pk_bf16_f32 v67, v68, v69
	global_store_dwordx2 v[82:83], v[66:67], off offset:288
	v_lshl_add_u64 v[72:73], v[70:71], 2, s[14:15]
	global_load_dwordx4 v[66:69], v[72:73], off
	global_load_dwordx4 v[206:209], v[72:73], off offset:64
	global_load_dwordx4 v[210:213], v[72:73], off offset:512
	global_load_dwordx4 v[214:217], v[72:73], off offset:576
	s_mov_b64 s[16:17], 0x48000
	s_waitcnt vmcnt(3)
	v_pk_fma_f32 v[64:65], v[64:65], v[120:121], v[68:69]
	v_pk_fma_f32 v[62:63], v[62:63], v[118:119], v[66:67]
	v_lshl_add_u64 v[66:67], v[70:71], 1, s[4:5]
	v_cvt_pk_bf16_f32 v62, v62, v63
	v_cvt_pk_bf16_f32 v63, v64, v65
	global_store_dwordx2 v[66:67], v[62:63], off
	s_waitcnt vmcnt(3)
	v_pk_fma_f32 v[60:61], v[60:61], v[108:109], v[208:209]
	v_pk_fma_f32 v[58:59], v[58:59], v[106:107], v[206:207]
	s_nop 0
	v_cvt_pk_bf16_f32 v58, v58, v59
	v_cvt_pk_bf16_f32 v59, v60, v61
	global_store_dwordx2 v[66:67], v[58:59], off offset:32
	s_waitcnt vmcnt(3)
	v_pk_fma_f32 v[56:57], v[56:57], v[104:105], v[212:213]
	v_pk_fma_f32 v[54:55], v[54:55], v[102:103], v[210:211]
	s_nop 0
	v_cvt_pk_bf16_f32 v54, v54, v55
	v_cvt_pk_bf16_f32 v55, v56, v57
	global_store_dwordx2 v[66:67], v[54:55], off offset:256
	s_waitcnt vmcnt(3)
	v_pk_fma_f32 v[52:53], v[52:53], v[100:101], v[216:217]
	v_pk_fma_f32 v[50:51], v[50:51], v[98:99], v[214:215]
	v_lshl_add_u64 v[54:55], v[146:147], 0, s[16:17]
	v_cvt_pk_bf16_f32 v50, v50, v51
	v_cvt_pk_bf16_f32 v51, v52, v53
	global_store_dwordx2 v[66:67], v[50:51], off offset:288
	v_lshl_add_u64 v[56:57], v[54:55], 2, s[14:15]
	global_load_dwordx4 v[50:53], v[56:57], off
	global_load_dwordx4 v[206:209], v[56:57], off offset:64
	global_load_dwordx4 v[210:213], v[56:57], off offset:512
	global_load_dwordx4 v[214:217], v[56:57], off offset:576
	s_mov_b64 s[16:17], 0x50000
	s_waitcnt vmcnt(3)
	v_pk_fma_f32 v[48:49], v[48:49], v[120:121], v[52:53]
	v_pk_fma_f32 v[46:47], v[46:47], v[118:119], v[50:51]
	v_lshl_add_u64 v[50:51], v[54:55], 1, s[4:5]
	v_cvt_pk_bf16_f32 v46, v46, v47
	v_cvt_pk_bf16_f32 v47, v48, v49
	global_store_dwordx2 v[50:51], v[46:47], off
	s_waitcnt vmcnt(3)
	v_pk_fma_f32 v[44:45], v[44:45], v[108:109], v[208:209]
	v_pk_fma_f32 v[42:43], v[42:43], v[106:107], v[206:207]
	s_nop 0
	v_cvt_pk_bf16_f32 v42, v42, v43
	v_cvt_pk_bf16_f32 v43, v44, v45
	global_store_dwordx2 v[50:51], v[42:43], off offset:32
	s_waitcnt vmcnt(3)
	v_pk_fma_f32 v[40:41], v[40:41], v[104:105], v[212:213]
	v_pk_fma_f32 v[38:39], v[38:39], v[102:103], v[210:211]
	s_nop 0
	v_cvt_pk_bf16_f32 v38, v38, v39
	v_cvt_pk_bf16_f32 v39, v40, v41
	global_store_dwordx2 v[50:51], v[38:39], off offset:256
	s_waitcnt vmcnt(3)
	v_pk_fma_f32 v[36:37], v[36:37], v[100:101], v[216:217]
	v_pk_fma_f32 v[34:35], v[34:35], v[98:99], v[214:215]
	v_lshl_add_u64 v[38:39], v[146:147], 0, s[16:17]
	v_cvt_pk_bf16_f32 v34, v34, v35
	v_cvt_pk_bf16_f32 v35, v36, v37
	global_store_dwordx2 v[50:51], v[34:35], off offset:288
	v_lshl_add_u64 v[40:41], v[38:39], 2, s[14:15]
	global_load_dwordx4 v[34:37], v[40:41], off
	global_load_dwordx4 v[206:209], v[40:41], off offset:64
	global_load_dwordx4 v[210:213], v[40:41], off offset:512
	global_load_dwordx4 v[214:217], v[40:41], off offset:576
	s_mov_b64 s[16:17], 0x58000
	s_waitcnt vmcnt(3)
	v_pk_fma_f32 v[32:33], v[32:33], v[120:121], v[36:37]
	v_pk_fma_f32 v[30:31], v[30:31], v[118:119], v[34:35]
	v_lshl_add_u64 v[34:35], v[38:39], 1, s[4:5]
	v_cvt_pk_bf16_f32 v30, v30, v31
	v_cvt_pk_bf16_f32 v31, v32, v33
	global_store_dwordx2 v[34:35], v[30:31], off
	s_waitcnt vmcnt(3)
	v_pk_fma_f32 v[28:29], v[28:29], v[108:109], v[208:209]
	v_pk_fma_f32 v[26:27], v[26:27], v[106:107], v[206:207]
	s_nop 0
	v_cvt_pk_bf16_f32 v26, v26, v27
	v_cvt_pk_bf16_f32 v27, v28, v29
	global_store_dwordx2 v[34:35], v[26:27], off offset:32
	s_waitcnt vmcnt(3)
	v_pk_fma_f32 v[24:25], v[24:25], v[104:105], v[212:213]
	v_pk_fma_f32 v[22:23], v[22:23], v[102:103], v[210:211]
	s_nop 0
	v_cvt_pk_bf16_f32 v22, v22, v23
	v_cvt_pk_bf16_f32 v23, v24, v25
	global_store_dwordx2 v[34:35], v[22:23], off offset:256
	s_waitcnt vmcnt(3)
	v_pk_fma_f32 v[20:21], v[20:21], v[100:101], v[216:217]
	v_pk_fma_f32 v[18:19], v[18:19], v[98:99], v[214:215]
	v_lshl_add_u64 v[22:23], v[146:147], 0, s[16:17]
	v_cvt_pk_bf16_f32 v18, v18, v19
	v_cvt_pk_bf16_f32 v19, v20, v21
	global_store_dwordx2 v[34:35], v[18:19], off offset:288
	v_lshl_add_u64 v[24:25], v[22:23], 2, s[14:15]
	global_load_dwordx4 v[18:21], v[24:25], off
	global_load_dwordx4 v[206:209], v[24:25], off offset:64
	global_load_dwordx4 v[210:213], v[24:25], off offset:512
	global_load_dwordx4 v[214:217], v[24:25], off offset:576
	s_waitcnt vmcnt(3)
	v_pk_fma_f32 v[16:17], v[16:17], v[120:121], v[20:21]
	v_pk_fma_f32 v[14:15], v[14:15], v[118:119], v[18:19]
	v_lshl_add_u64 v[18:19], v[22:23], 1, s[4:5]
	v_cvt_pk_bf16_f32 v14, v14, v15
	v_cvt_pk_bf16_f32 v15, v16, v17
	global_store_dwordx2 v[18:19], v[14:15], off
	s_waitcnt vmcnt(3)
	v_pk_fma_f32 v[12:13], v[12:13], v[108:109], v[208:209]
	v_pk_fma_f32 v[10:11], v[10:11], v[106:107], v[206:207]
	s_nop 0
	v_cvt_pk_bf16_f32 v10, v10, v11
	v_cvt_pk_bf16_f32 v11, v12, v13
	global_store_dwordx2 v[18:19], v[10:11], off offset:32
	s_waitcnt vmcnt(3)
	v_pk_fma_f32 v[8:9], v[8:9], v[104:105], v[212:213]
	v_pk_fma_f32 v[6:7], v[6:7], v[102:103], v[210:211]
	s_nop 0
	v_cvt_pk_bf16_f32 v6, v6, v7
	v_cvt_pk_bf16_f32 v7, v8, v9
	global_store_dwordx2 v[18:19], v[6:7], off offset:256
	s_waitcnt vmcnt(3)
	v_pk_fma_f32 v[4:5], v[4:5], v[100:101], v[216:217]
	v_pk_fma_f32 v[2:3], v[2:3], v[98:99], v[214:215]
	s_nop 0
	v_cvt_pk_bf16_f32 v2, v2, v3
	v_cvt_pk_bf16_f32 v3, v4, v5
	global_store_dwordx2 v[18:19], v[2:3], off offset:288
	s_mov_b64 s[14:15], -1
	s_and_b64 vcc, exec, s[2:3]
	s_cbranch_vccz .LBB0_1443

; #define PG8_STAGE(bufoff, gbase, voff) do { _Pragma("unroll") for (int _i = 0; _i < 2; ++_i) \
;         __builtin_amdgcn_global_load_lds((const unsigned*)((const char*)(gbase) + (voff)[_i]), (LAS unsigned*)(lds + (bufoff) + ldsw + _i * 8192), 16, 0, 0); } while (0)
; #define PG8_LDA(dst, b, h) do { _Pragma("unroll") for (int m = 0; m < 4; ++m) _Pragma("unroll") for (int k = 0; k < 2; ++k) dst[m][k] = *(const LAS bf16x8*)(lds + PG8_SA(b, h) + aoff + m * 2048 + k * 1024); } while (0)
; #define PG8_LDB(dst, b, h) do { _Pragma("unroll") for (int n = 0; n < 2; ++n) _Pragma("unroll") for (int k = 0; k < 2; ++k) dst[n][k] = *(const LAS bf16x8*)(lds + PG8_SB(b, h) + boff + n * 2048 + k * 1024); } while (0)
; #define PG8_MMA(ai, bj, At, Bt) do { __builtin_amdgcn_s_setprio(1); _Pragma("unroll") for (int m = 0; m < 4; ++m) _Pragma("unroll") for (int n = 0; n < 2; ++n) _Pragma("unroll") for (int k = 0; k < 2; ++k) \
;         acc[ai][bj][m][n] = __builtin_amdgcn_mfma_f32_16x16x32_bf16(Bt[n][k], At[m][k], acc[ai][bj][m][n], 0, 0, 0); __builtin_amdgcn_s_setprio(0); } while (0)
; #define PG8_WAIT_V(n) asm volatile("s_waitcnt vmcnt(" #n ")" ::: "memory")
; #define PG8_WAIT_L(n) asm volatile("s_waitcnt lgkmcnt(" #n ")" ::: "memory")
; #define PG8_BAR __builtin_amdgcn_s_barrier()
; #define PG8_SCHED __builtin_amdgcn_sched_barrier(0)
; template <class Epi, class SchedT>
; DI void gemm_phase(LAS unsigned char* lds, const Gemm g, const SchedT& S, const Epi& E) {
;     ...
;             PG8_LDB(B0, 0, 0); PG8_SCHED; PG8_LDA(At, 0, 0); PG8_STAGE(PG8_SA(1, 1), a1 + hstepA, voffA);
;             PG8_WAIT_L(8); PG8_BAR; PG8_WAIT_L(0); PG8_MMA(0, 0, At, B0); PG8_BAR; PG8_SCHED;
;             PG8_LDB(B1, 0, 1); PG8_STAGE(PG8_SB(0, 0), b2, voffB);
;             PG8_BAR; PG8_WAIT_L(0); PG8_MMA(0, 1, At, B1); PG8_BAR;
;             PG8_LDA(At, 0, 1); PG8_STAGE(PG8_SA(0, 0), a2, voffA);
;             PG8_BAR; PG8_WAIT_L(0); PG8_MMA(1, 0, At, B0); PG8_BAR; PG8_SCHED;
;             PG8_STAGE(PG8_SB(0, 1), b2 + hstepB, voffB);
;             PG8_WAIT_V(6); PG8_BAR; PG8_MMA(1, 1, At, B1); PG8_BAR;
.LBB0_1705:
	s_add_u32 s10, s8, 0xffea0080
	s_addc_u32 s11, s9, -1
	s_add_i32 s42, 0, 0x10000
	v_add_u32_e32 v36, s42, v150
	ds_read_b128 v[46:49], v36
	ds_read_b128 v[54:57], v36 offset:1024
	ds_read_b128 v[62:65], v36 offset:2048
	ds_read_b128 v[152:155], v36 offset:3072
	s_cmpk_eq_i32 s41, 0x54
	s_cselect_b32 s13, s7, s11
	s_cselect_b32 s12, s6, s10
	s_cselect_b32 s11, s1, s40
	s_cselect_b32 s10, s0, s39
	v_lshl_add_u64 v[36:37], s[8:9], 0, v[0:1]
	s_add_i32 m0, s24, 0xc000
	ds_read_b128 v[156:159], v151
	ds_read_b128 v[160:163], v151 offset:1024
	ds_read_b128 v[164:167], v151 offset:2048
	ds_read_b128 v[168:171], v151 offset:3072
	ds_read_b128 v[172:175], v151 offset:4096
	ds_read_b128 v[176:179], v151 offset:5120
	ds_read_b128 v[184:187], v151 offset:6144
	ds_read_b128 v[188:191], v151 offset:7168
	global_load_lds_dwordx4 v[36:37], off
	v_lshl_add_u64 v[36:37], s[8:9], 0, v[34:35]
	s_add_i32 m0, s24, 0xe000
	s_nop 0
	global_load_lds_dwordx4 v[36:37], off
	s_waitcnt lgkmcnt(8)
	s_barrier
	s_waitcnt lgkmcnt(0)
	s_setprio 1
	s_waitcnt lgkmcnt(0)
	v_mfma_f32_16x16x32_bf16 v[142:145], v[46:49], v[156:159], v[142:145]
	v_mfma_f32_16x16x32_bf16 v[138:141], v[62:65], v[156:159], v[138:141]
	v_mfma_f32_16x16x32_bf16 v[126:129], v[46:49], v[164:167], v[126:129]
	v_mfma_f32_16x16x32_bf16 v[122:125], v[62:65], v[164:167], v[122:125]
	v_mfma_f32_16x16x32_bf16 v[110:113], v[46:49], v[172:175], v[110:113]
	v_mfma_f32_16x16x32_bf16 v[106:109], v[62:65], v[172:175], v[106:109]
	v_mfma_f32_16x16x32_bf16 v[94:97], v[46:49], v[184:187], v[94:97]
	v_mfma_f32_16x16x32_bf16 v[90:93], v[62:65], v[184:187], v[90:93]
	v_mfma_f32_16x16x32_bf16 v[142:145], v[54:57], v[160:163], v[142:145]
	v_mfma_f32_16x16x32_bf16 v[138:141], v[152:155], v[160:163], v[138:141]
	v_mfma_f32_16x16x32_bf16 v[126:129], v[54:57], v[168:171], v[126:129]
	v_mfma_f32_16x16x32_bf16 v[122:125], v[152:155], v[168:171], v[122:125]
	v_mfma_f32_16x16x32_bf16 v[110:113], v[54:57], v[176:179], v[110:113]
	v_mfma_f32_16x16x32_bf16 v[106:109], v[152:155], v[176:179], v[106:109]
	v_mfma_f32_16x16x32_bf16 v[94:97], v[54:57], v[188:191], v[94:97]
	v_mfma_f32_16x16x32_bf16 v[90:93], v[152:155], v[188:191], v[90:93]
	s_setprio 0
	s_barrier
	s_add_i32 s44, 0, 0x14000
	s_add_i32 s42, s42, s18
	v_add_u32_e32 v36, s44, v150
	v_lshl_add_u64 v[146:147], s[10:11], 0, v[0:1]
	s_mov_b32 m0, s42
	ds_read_b128 v[202:205], v36
	ds_read_b128 v[206:209], v36 offset:1024
	ds_read_b128 v[210:213], v36 offset:2048
	ds_read_b128 v[214:217], v36 offset:3072
	global_load_lds_dwordx4 v[146:147], off
	v_lshl_add_u64 v[180:181], s[10:11], 0, v[34:35]
	s_add_i32 m0, s42, 0x2000
	s_nop 0
	global_load_lds_dwordx4 v[180:181], off
	s_barrier
	s_waitcnt lgkmcnt(0)
	s_setprio 1
	s_waitcnt lgkmcnt(0)
	v_mfma_f32_16x16x32_bf16 v[134:137], v[202:205], v[156:159], v[134:137]
	v_mfma_f32_16x16x32_bf16 v[130:133], v[210:213], v[156:159], v[130:133]
	v_mfma_f32_16x16x32_bf16 v[118:121], v[202:205], v[164:167], v[118:121]
	v_mfma_f32_16x16x32_bf16 v[114:117], v[210:213], v[164:167], v[114:117]
	v_mfma_f32_16x16x32_bf16 v[102:105], v[202:205], v[172:175], v[102:105]
	v_mfma_f32_16x16x32_bf16 v[98:101], v[210:213], v[172:175], v[98:101]
	v_mfma_f32_16x16x32_bf16 v[86:89], v[202:205], v[184:187], v[86:89]
	v_mfma_f32_16x16x32_bf16 v[82:85], v[210:213], v[184:187], v[82:85]
	v_mfma_f32_16x16x32_bf16 v[134:137], v[206:209], v[160:163], v[134:137]
	v_mfma_f32_16x16x32_bf16 v[130:133], v[214:217], v[160:163], v[130:133]
	v_mfma_f32_16x16x32_bf16 v[118:121], v[206:209], v[168:171], v[118:121]
	v_mfma_f32_16x16x32_bf16 v[114:117], v[214:217], v[168:171], v[114:117]
	v_mfma_f32_16x16x32_bf16 v[102:105], v[206:209], v[176:179], v[102:105]
	v_mfma_f32_16x16x32_bf16 v[98:101], v[214:217], v[176:179], v[98:101]
	v_mfma_f32_16x16x32_bf16 v[86:89], v[206:209], v[188:191], v[86:89]
	v_mfma_f32_16x16x32_bf16 v[82:85], v[214:217], v[188:191], v[82:85]
	s_setprio 0
	s_mov_b32 m0, s24
	v_lshl_add_u64 v[182:183], s[12:13], 0, v[0:1]
	s_barrier
	ds_read_b128 v[156:159], v151 offset:16384
	ds_read_b128 v[160:163], v151 offset:17408
	ds_read_b128 v[164:167], v151 offset:18432
	ds_read_b128 v[168:171], v151 offset:19456
	ds_read_b128 v[172:175], v151 offset:20480
	ds_read_b128 v[176:179], v151 offset:21504
	ds_read_b128 v[184:187], v151 offset:22528
	ds_read_b128 v[188:191], v151 offset:23552
	global_load_lds_dwordx4 v[182:183], off
	v_lshl_add_u64 v[194:195], s[12:13], 0, v[34:35]
	s_mov_b32 m0, s25
	s_nop 0
	global_load_lds_dwordx4 v[194:195], off
	s_barrier
	s_waitcnt lgkmcnt(0)
	s_setprio 1
	s_waitcnt lgkmcnt(0)
	v_mfma_f32_16x16x32_bf16 v[78:81], v[46:49], v[156:159], v[78:81]
	v_mfma_f32_16x16x32_bf16 v[74:77], v[62:65], v[156:159], v[74:77]
	v_mfma_f32_16x16x32_bf16 v[58:61], v[46:49], v[164:167], v[58:61]
	v_mfma_f32_16x16x32_bf16 v[50:53], v[62:65], v[164:167], v[50:53]
	v_mfma_f32_16x16x32_bf16 v[30:33], v[46:49], v[172:175], v[30:33]
	v_mfma_f32_16x16x32_bf16 v[26:29], v[62:65], v[172:175], v[26:29]
	v_mfma_f32_16x16x32_bf16 v[14:17], v[46:49], v[184:187], v[14:17]
	v_mfma_f32_16x16x32_bf16 v[10:13], v[62:65], v[184:187], v[10:13]
	v_mfma_f32_16x16x32_bf16 v[78:81], v[54:57], v[160:163], v[78:81]
	v_mfma_f32_16x16x32_bf16 v[74:77], v[152:155], v[160:163], v[74:77]
	v_mfma_f32_16x16x32_bf16 v[58:61], v[54:57], v[168:171], v[58:61]
	v_mfma_f32_16x16x32_bf16 v[50:53], v[152:155], v[168:171], v[50:53]
	v_mfma_f32_16x16x32_bf16 v[30:33], v[54:57], v[176:179], v[30:33]
	v_mfma_f32_16x16x32_bf16 v[26:29], v[152:155], v[176:179], v[26:29]
	v_mfma_f32_16x16x32_bf16 v[14:17], v[54:57], v[188:191], v[14:17]
	v_mfma_f32_16x16x32_bf16 v[10:13], v[152:155], v[188:191], v[10:13]
	s_setprio 0
	s_barrier
; #define PG8_STAGE(bufoff, gbase, voff) do { _Pragma("unroll") for (int _i = 0; _i < 2; ++_i) \
;         __builtin_amdgcn_global_load_lds((const unsigned*)((const char*)(gbase) + (voff)[_i]), (LAS unsigned*)(lds + (bufoff) + ldsw + _i * 8192), 16, 0, 0); } while (0)
; #define PG8_LDA(dst, b, h) do { _Pragma("unroll") for (int m = 0; m < 4; ++m) _Pragma("unroll") for (int k = 0; k < 2; ++k) dst[m][k] = *(const LAS bf16x8*)(lds + PG8_SA(b, h) + aoff + m * 2048 + k * 1024); } while (0)
; #define PG8_LDB(dst, b, h) do { _Pragma("unroll") for (int n = 0; n < 2; ++n) _Pragma("unroll") for (int k = 0; k < 2; ++k) dst[n][k] = *(const LAS bf16x8*)(lds + PG8_SB(b, h) + boff + n * 2048 + k * 1024); } while (0)
; #define PG8_MMA(ai, bj, At, Bt) do { __builtin_amdgcn_s_setprio(1); _Pragma("unroll") for (int m = 0; m < 4; ++m) _Pragma("unroll") for (int n = 0; n < 2; ++n) _Pragma("unroll") for (int k = 0; k < 2; ++k) \
;         acc[ai][bj][m][n] = __builtin_amdgcn_mfma_f32_16x16x32_bf16(Bt[n][k], At[m][k], acc[ai][bj][m][n], 0, 0, 0); __builtin_amdgcn_s_setprio(0); } while (0)
; #define PG8_WAIT_V(n) asm volatile("s_waitcnt vmcnt(" #n ")" ::: "memory")
; #define PG8_WAIT_L(n) asm volatile("s_waitcnt lgkmcnt(" #n ")" ::: "memory")
; #define PG8_BAR __builtin_amdgcn_s_barrier()
; #define PG8_SCHED __builtin_amdgcn_sched_barrier(0)
; template <class Epi, class SchedT>
; DI void gemm_phase(LAS unsigned char* lds, const Gemm g, const SchedT& S, const Epi& E) {
;     ...
;             PG8_STAGE(PG8_SB(0, 1), b2 + hstepB, voffB);
;             PG8_WAIT_V(6); PG8_BAR; PG8_MMA(1, 1, At, B1); PG8_BAR;
;             PG8_LDB(B0, 1, 0); PG8_SCHED; PG8_LDA(At, 1, 0); PG8_STAGE(PG8_SA(0, 1), a2 + hstepA, voffA);
;             PG8_WAIT_L(8); PG8_BAR; PG8_WAIT_L(0); PG8_MMA(0, 0, At, B0); PG8_BAR; PG8_SCHED;
;             PG8_LDB(B1, 1, 1); PG8_STAGE(PG8_SB(1, 0), b3, voffB);
;             PG8_BAR; PG8_WAIT_L(0); PG8_MMA(0, 1, At, B1); PG8_BAR;
;             PG8_LDA(At, 1, 1); PG8_STAGE(PG8_SA(1, 0), a3, voffA);
	s_add_u32 s42, s10, 0x160000
	s_addc_u32 s43, s11, 0
	s_add_i32 s44, s44, s18
	v_lshl_add_u64 v[36:37], s[42:43], 0, v[0:1]
	s_mov_b32 m0, s44
	s_nop 0
	global_load_lds_dwordx4 v[36:37], off
	v_lshl_add_u64 v[36:37], s[42:43], 0, v[34:35]
	s_add_i32 m0, s44, 0x2000
	s_nop 0
	global_load_lds_dwordx4 v[36:37], off
	s_waitcnt vmcnt(6)
	s_barrier
	s_setprio 1
	v_mfma_f32_16x16x32_bf16 v[42:45], v[202:205], v[164:167], v[42:45]
	v_mfma_f32_16x16x32_bf16 v[36:39], v[210:213], v[164:167], v[38:41]
	v_mfma_f32_16x16x32_bf16 v[22:25], v[202:205], v[172:175], v[22:25]
	v_mfma_f32_16x16x32_bf16 v[18:21], v[210:213], v[172:175], v[18:21]
	v_mfma_f32_16x16x32_bf16 v[6:9], v[202:205], v[184:187], v[6:9]
	v_mfma_f32_16x16x32_bf16 v[2:5], v[210:213], v[184:187], v[2:5]
	v_mfma_f32_16x16x32_bf16 v[46:49], v[202:205], v[156:159], v[70:73]
	v_mfma_f32_16x16x32_bf16 v[54:57], v[210:213], v[156:159], v[66:69]
	v_mfma_f32_16x16x32_bf16 v[42:45], v[206:209], v[168:171], v[42:45]
	v_mfma_f32_16x16x32_bf16 v[36:39], v[214:217], v[168:171], v[36:39]
	v_mfma_f32_16x16x32_bf16 v[22:25], v[206:209], v[176:179], v[22:25]
	v_mfma_f32_16x16x32_bf16 v[18:21], v[214:217], v[176:179], v[18:21]
	v_mfma_f32_16x16x32_bf16 v[6:9], v[206:209], v[188:191], v[6:9]
	v_mfma_f32_16x16x32_bf16 v[2:5], v[214:217], v[188:191], v[2:5]
	v_mfma_f32_16x16x32_bf16 v[46:49], v[206:209], v[160:163], v[46:49]
	v_mfma_f32_16x16x32_bf16 v[54:57], v[214:217], v[160:163], v[54:57]
	s_setprio 0
	s_add_i32 s42, 0, 0x18000
	v_add_u32_e32 v40, s42, v150
	s_barrier
	ds_read_b128 v[62:65], v40
	ds_read_b128 v[66:69], v40 offset:1024
	ds_read_b128 v[70:73], v40 offset:2048
	ds_read_b128 v[152:155], v40 offset:3072
	s_add_u32 s12, s12, 0x160000
	s_addc_u32 s13, s13, 0
	s_mov_b32 m0, s26
	v_lshl_add_u64 v[40:41], s[12:13], 0, v[0:1]
	ds_read_b128 v[156:159], v151 offset:32768
	ds_read_b128 v[160:163], v151 offset:33792
	ds_read_b128 v[164:167], v151 offset:34816
	ds_read_b128 v[168:171], v151 offset:35840
	ds_read_b128 v[172:175], v151 offset:36864
	ds_read_b128 v[176:179], v151 offset:37888
	ds_read_b128 v[184:187], v151 offset:38912
	ds_read_b128 v[188:191], v151 offset:39936
	global_load_lds_dwordx4 v[40:41], off
	v_lshl_add_u64 v[40:41], s[12:13], 0, v[34:35]
	s_mov_b32 m0, s27
	s_nop 0
	global_load_lds_dwordx4 v[40:41], off
	s_waitcnt lgkmcnt(8)
	s_barrier
	s_waitcnt lgkmcnt(0)
	s_setprio 1
	s_waitcnt lgkmcnt(0)
	v_mfma_f32_16x16x32_bf16 v[142:145], v[62:65], v[156:159], v[142:145]
	v_mfma_f32_16x16x32_bf16 v[138:141], v[70:73], v[156:159], v[138:141]
	v_mfma_f32_16x16x32_bf16 v[126:129], v[62:65], v[164:167], v[126:129]
	v_mfma_f32_16x16x32_bf16 v[122:125], v[70:73], v[164:167], v[122:125]
	v_mfma_f32_16x16x32_bf16 v[110:113], v[62:65], v[172:175], v[110:113]
	v_mfma_f32_16x16x32_bf16 v[106:109], v[70:73], v[172:175], v[106:109]
	v_mfma_f32_16x16x32_bf16 v[94:97], v[62:65], v[184:187], v[94:97]
	v_mfma_f32_16x16x32_bf16 v[90:93], v[70:73], v[184:187], v[90:93]
	v_mfma_f32_16x16x32_bf16 v[142:145], v[66:69], v[160:163], v[142:145]
	v_mfma_f32_16x16x32_bf16 v[138:141], v[152:155], v[160:163], v[138:141]
	v_mfma_f32_16x16x32_bf16 v[126:129], v[66:69], v[168:171], v[126:129]
	v_mfma_f32_16x16x32_bf16 v[122:125], v[152:155], v[168:171], v[122:125]
	v_mfma_f32_16x16x32_bf16 v[110:113], v[66:69], v[176:179], v[110:113]
	v_mfma_f32_16x16x32_bf16 v[106:109], v[152:155], v[176:179], v[106:109]
	v_mfma_f32_16x16x32_bf16 v[94:97], v[66:69], v[188:191], v[94:97]
	v_mfma_f32_16x16x32_bf16 v[90:93], v[152:155], v[188:191], v[90:93]
	s_setprio 0
	s_barrier
	s_add_i32 s12, 0, 0x1c000
	v_add_u32_e32 v40, s12, v150
	s_add_i32 s13, s42, s18
	ds_read_b128 v[202:205], v40
	ds_read_b128 v[206:209], v40 offset:1024
	ds_read_b128 v[210:213], v40 offset:2048
	ds_read_b128 v[214:217], v40 offset:3072
	v_lshl_add_u64 v[40:41], v[146:147], 0, s[90:91]
	s_mov_b32 m0, s13
	s_nop 0
	global_load_lds_dwordx4 v[40:41], off
	v_lshl_add_u64 v[40:41], v[180:181], 0, s[90:91]
	s_add_i32 m0, s13, 0x2000
	s_nop 0
	global_load_lds_dwordx4 v[40:41], off
	s_barrier
	s_waitcnt lgkmcnt(0)
	s_setprio 1
	s_waitcnt lgkmcnt(0)
	v_mfma_f32_16x16x32_bf16 v[134:137], v[202:205], v[156:159], v[134:137]
	v_mfma_f32_16x16x32_bf16 v[130:133], v[210:213], v[156:159], v[130:133]
	v_mfma_f32_16x16x32_bf16 v[118:121], v[202:205], v[164:167], v[118:121]
	v_mfma_f32_16x16x32_bf16 v[114:117], v[210:213], v[164:167], v[114:117]
	v_mfma_f32_16x16x32_bf16 v[102:105], v[202:205], v[172:175], v[102:105]
	v_mfma_f32_16x16x32_bf16 v[98:101], v[210:213], v[172:175], v[98:101]
	v_mfma_f32_16x16x32_bf16 v[86:89], v[202:205], v[184:187], v[86:89]
	v_mfma_f32_16x16x32_bf16 v[82:85], v[210:213], v[184:187], v[82:85]
	v_mfma_f32_16x16x32_bf16 v[134:137], v[206:209], v[160:163], v[134:137]
	v_mfma_f32_16x16x32_bf16 v[130:133], v[214:217], v[160:163], v[130:133]
	v_mfma_f32_16x16x32_bf16 v[118:121], v[206:209], v[168:171], v[118:121]
	v_mfma_f32_16x16x32_bf16 v[114:117], v[214:217], v[168:171], v[114:117]
	v_mfma_f32_16x16x32_bf16 v[102:105], v[206:209], v[176:179], v[102:105]
	v_mfma_f32_16x16x32_bf16 v[98:101], v[214:217], v[176:179], v[98:101]
	v_mfma_f32_16x16x32_bf16 v[86:89], v[206:209], v[188:191], v[86:89]
	v_mfma_f32_16x16x32_bf16 v[82:85], v[214:217], v[188:191], v[82:85]
	s_setprio 0
	s_mov_b32 m0, s31
	v_lshl_add_u64 v[40:41], v[182:183], 0, s[90:91]
	s_barrier
	ds_read_b128 v[156:159], v151 offset:49152
	ds_read_b128 v[160:163], v151 offset:50176
	ds_read_b128 v[164:167], v151 offset:51200
	ds_read_b128 v[168:171], v151 offset:52224
	ds_read_b128 v[172:175], v151 offset:53248
	ds_read_b128 v[176:179], v151 offset:54272
	ds_read_b128 v[184:187], v151 offset:55296
	ds_read_b128 v[188:191], v151 offset:56320
	global_load_lds_dwordx4 v[40:41], off
	v_lshl_add_u64 v[40:41], v[194:195], 0, s[90:91]
	s_mov_b32 m0, s34
	s_nop 0
	global_load_lds_dwordx4 v[40:41], off
	s_barrier
; DI unsigned pk2(float a, float b) { f32x2 v = {a, b}; bfv2 r = __builtin_convertvector(v, bfv2); return __builtin_bit_cast(unsigned, r); }
; #define PG8_STAGE(bufoff, gbase, voff) do { _Pragma("unroll") for (int _i = 0; _i < 2; ++_i) \
;         __builtin_amdgcn_global_load_lds((const unsigned*)((const char*)(gbase) + (voff)[_i]), (LAS unsigned*)(lds + (bufoff) + ldsw + _i * 8192), 16, 0, 0); } while (0)
; #define PG8_MMA(ai, bj, At, Bt) do { __builtin_amdgcn_s_setprio(1); _Pragma("unroll") for (int m = 0; m < 4; ++m) _Pragma("unroll") for (int n = 0; n < 2; ++n) _Pragma("unroll") for (int k = 0; k < 2; ++k) \
;         acc[ai][bj][m][n] = __builtin_amdgcn_mfma_f32_16x16x32_bf16(Bt[n][k], At[m][k], acc[ai][bj][m][n], 0, 0, 0); __builtin_amdgcn_s_setprio(0); } while (0)
; template <class Epi, class SchedT>
; DI void gemm_phase(LAS unsigned char* lds, const Gemm g, const SchedT& S, const Epi& E) {
;     ...
;             PG8_BAR; PG8_WAIT_L(0); PG8_MMA(1, 0, At, B0); PG8_BAR; PG8_SCHED;
;             PG8_STAGE(PG8_SB(1, 1), b3 + hstepB, voffB);
;             PG8_WAIT_V(6); PG8_BAR; PG8_MMA(1, 1, At, B1); PG8_BAR;
;     DI void operator()(AccRef acc, const Unit& u, int wr, int wc, int fr, int fq) const {
;         const int row0 = u.pm * 256; const int midx = row0 < ML ? (row0 >> 12) : 4;
;         const float* src = row0 < ML ? xl : (xc - (size_t)ML * D);
;         const float* gp = gate + (size_t)midx * 12288;
;         const int col0 = u.pn * 256 + wc * 32 + 4 * fq;
;         f32x4 gv[2][2];
; #pragma unroll
;         for (int bj = 0; bj < 2; ++bj)
; #pragma unroll
;             for (int n = 0; n < 2; ++n) gv[bj][n] = *(const f32x4*)(gp + col0 + bj * 128 + n * 16);
;         if (xb) {
; #pragma unroll
;             for (int ai = 0; ai < 2; ++ai)
; #pragma unroll
;                 for (int m = 0; m < 4; ++m) { const size_t off = (size_t)(row0 + wr * 64 + fr + ai * 128 + m * 16) * D + col0;
; #pragma unroll
;                     for (int bj = 0; bj < 2; ++bj)
; #pragma unroll
;                         for (int n = 0; n < 2; ++n) { const size_t o2 = off + bj * 128 + n * 16;
;                             const f32x4 r = bf4(*(const u32x2*)(xb + o2)) + gv[bj][n] * acc[ai][bj][m][n];
;                             u32x2 w; w.x = pk2(r[0], r[1]); w.y = pk2(r[2], r[3]); *(u32x2*)(out + o2) = w; }
;                     asm volatile("" ::: "memory"); }
	s_waitcnt lgkmcnt(0)
	s_setprio 1
	s_waitcnt lgkmcnt(0)
	v_mfma_f32_16x16x32_bf16 v[78:81], v[62:65], v[156:159], v[78:81]
	v_mfma_f32_16x16x32_bf16 v[74:77], v[70:73], v[156:159], v[74:77]
	v_mfma_f32_16x16x32_bf16 v[58:61], v[62:65], v[164:167], v[58:61]
	v_mfma_f32_16x16x32_bf16 v[50:53], v[70:73], v[164:167], v[50:53]
	v_mfma_f32_16x16x32_bf16 v[30:33], v[62:65], v[172:175], v[30:33]
	v_mfma_f32_16x16x32_bf16 v[26:29], v[70:73], v[172:175], v[26:29]
	v_mfma_f32_16x16x32_bf16 v[14:17], v[62:65], v[184:187], v[14:17]
	v_mfma_f32_16x16x32_bf16 v[10:13], v[70:73], v[184:187], v[10:13]
	v_mfma_f32_16x16x32_bf16 v[78:81], v[66:69], v[160:163], v[78:81]
	v_mfma_f32_16x16x32_bf16 v[74:77], v[152:155], v[160:163], v[74:77]
	v_mfma_f32_16x16x32_bf16 v[58:61], v[66:69], v[168:171], v[58:61]
	v_mfma_f32_16x16x32_bf16 v[50:53], v[152:155], v[168:171], v[50:53]
	v_mfma_f32_16x16x32_bf16 v[30:33], v[66:69], v[176:179], v[30:33]
	v_mfma_f32_16x16x32_bf16 v[26:29], v[152:155], v[176:179], v[26:29]
	v_mfma_f32_16x16x32_bf16 v[14:17], v[66:69], v[188:191], v[14:17]
	v_mfma_f32_16x16x32_bf16 v[10:13], v[152:155], v[188:191], v[10:13]
	s_setprio 0
	s_barrier
	s_add_u32 s10, s10, 0x160080
	s_addc_u32 s11, s11, 0
	s_add_i32 s12, s12, s18
	v_lshl_add_u64 v[40:41], s[10:11], 0, v[0:1]
	s_mov_b32 m0, s12
	s_nop 0
	global_load_lds_dwordx4 v[40:41], off
	v_lshl_add_u64 v[40:41], s[10:11], 0, v[34:35]
	s_add_i32 m0, s12, 0x2000
	s_nop 0
	global_load_lds_dwordx4 v[40:41], off
	s_waitcnt vmcnt(6)
	s_barrier
	s_setprio 1
	v_mfma_f32_16x16x32_bf16 v[46:49], v[202:205], v[156:159], v[46:49]
	v_mfma_f32_16x16x32_bf16 v[70:73], v[206:209], v[160:163], v[46:49]
	v_mfma_f32_16x16x32_bf16 v[46:49], v[210:213], v[156:159], v[54:57]
	v_mfma_f32_16x16x32_bf16 v[40:43], v[202:205], v[164:167], v[42:45]
	v_mfma_f32_16x16x32_bf16 v[36:39], v[210:213], v[164:167], v[36:39]
	v_mfma_f32_16x16x32_bf16 v[22:25], v[202:205], v[172:175], v[22:25]
	v_mfma_f32_16x16x32_bf16 v[18:21], v[210:213], v[172:175], v[18:21]
	v_mfma_f32_16x16x32_bf16 v[6:9], v[202:205], v[184:187], v[6:9]
	v_mfma_f32_16x16x32_bf16 v[2:5], v[210:213], v[184:187], v[2:5]
	v_mfma_f32_16x16x32_bf16 v[66:69], v[214:217], v[160:163], v[46:49]
	v_mfma_f32_16x16x32_bf16 v[42:45], v[206:209], v[168:171], v[40:43]
	v_mfma_f32_16x16x32_bf16 v[38:41], v[214:217], v[168:171], v[36:39]
	v_mfma_f32_16x16x32_bf16 v[22:25], v[206:209], v[176:179], v[22:25]
	v_mfma_f32_16x16x32_bf16 v[18:21], v[214:217], v[176:179], v[18:21]
	v_mfma_f32_16x16x32_bf16 v[6:9], v[206:209], v[188:191], v[6:9]
	v_mfma_f32_16x16x32_bf16 v[2:5], v[214:217], v[188:191], v[2:5]
	s_setprio 0
	s_add_i32 s41, s41, 2
	s_add_u32 s8, s8, 0x100
	s_addc_u32 s9, s9, 0
	s_add_u32 s39, s39, 0x100
	s_addc_u32 s40, s40, 0
	s_cmpk_gt_u32 s41, 0x55
	s_barrier
	s_cbranch_scc0 .LBB0_1705
	s_min_i32 s8, s38, 64
	s_ashr_i32 s8, s8, 4
	v_mov_b32_e32 v0, v149
	s_mov_b32 s10, s30
	v_mov_b32_e32 v152, v148
	s_mov_b32 s11, s17
	s_lshl_b32 s12, s38, 8
	s_mul_hi_i32 s9, s8, 0xc000
	s_mul_i32 s8, s8, 0xc000
	s_add_u32 s8, s28, s8
	s_addc_u32 s9, s29, s9
	s_lshl_b32 s13, s33, 8
	s_lshl_b32 s10, s10, 5
	s_add_i32 s10, s10, s13
	v_lshl_add_u32 v146, v0, 2, s10
	v_ashrrev_i32_e32 v147, 31, v146
	v_lshl_add_u64 v[34:35], v[146:147], 2, s[8:9]
	s_lshl_b32 s8, s11, 6
	s_add_i32 s8, s8, s12
	v_add_u32_e32 v152, s8, v152
	v_ashrrev_i32_e32 v153, 31, v152
	v_lshlrev_b64 v[152:153], 12, v[152:153]
	v_lshl_add_u64 v[152:153], s[4:5], 0, v[152:153]
	v_lshl_add_u64 v[146:147], v[146:147], 1, v[152:153]
	global_load_dwordx4 v[62:65], v[34:35], off
	global_load_dwordx4 v[54:57], v[34:35], off offset:64
	global_load_dwordx4 v[46:49], v[34:35], off offset:512
	s_nop 0
	global_load_dwordx4 v[34:37], v[34:35], off offset:576
	s_mov_b64 s[8:9], 0x10000
	global_load_dwordx2 v[152:153], v[146:147], off
	global_load_dwordx2 v[206:207], v[146:147], off offset:32
	global_load_dwordx2 v[208:209], v[146:147], off offset:256
	global_load_dwordx2 v[210:211], v[146:147], off offset:288
	s_waitcnt vmcnt(3)
	v_lshlrev_b32_e32 v154, 16, v152
	v_and_b32_e32 v155, 0xffff0000, v152
	v_lshlrev_b32_e32 v152, 16, v153
	v_and_b32_e32 v153, 0xffff0000, v153
	v_pk_fma_f32 v[144:145], v[144:145], v[64:65], v[152:153]
	v_pk_fma_f32 v[142:143], v[142:143], v[62:63], v[154:155]
	s_nop 0
	v_cvt_pk_bf16_f32 v142, v142, v143
	v_cvt_pk_bf16_f32 v143, v144, v145
	global_store_dwordx2 v[146:147], v[142:143], off
	s_waitcnt vmcnt(3)
	v_lshlrev_b32_e32 v144, 16, v206
	v_and_b32_e32 v145, 0xffff0000, v206
	v_lshlrev_b32_e32 v142, 16, v207
	v_and_b32_e32 v143, 0xffff0000, v207
	v_pk_fma_f32 v[140:141], v[140:141], v[56:57], v[142:143]
	v_pk_fma_f32 v[138:139], v[138:139], v[54:55], v[144:145]
	s_nop 0
	v_cvt_pk_bf16_f32 v138, v138, v139
	v_cvt_pk_bf16_f32 v139, v140, v141
	global_store_dwordx2 v[146:147], v[138:139], off offset:32
	s_waitcnt vmcnt(3)
	v_lshlrev_b32_e32 v140, 16, v208
	v_and_b32_e32 v141, 0xffff0000, v208
	v_lshlrev_b32_e32 v138, 16, v209
	v_and_b32_e32 v139, 0xffff0000, v209
	v_pk_fma_f32 v[136:137], v[136:137], v[48:49], v[138:139]
	v_pk_fma_f32 v[134:135], v[134:135], v[46:47], v[140:141]
	s_nop 0
	v_cvt_pk_bf16_f32 v134, v134, v135
	v_cvt_pk_bf16_f32 v135, v136, v137
	global_store_dwordx2 v[146:147], v[134:135], off offset:256
	s_waitcnt vmcnt(3)
; DI unsigned pk2(float a, float b) { f32x2 v = {a, b}; bfv2 r = __builtin_convertvector(v, bfv2); return __builtin_bit_cast(unsigned, r); }
;     DI void operator()(AccRef acc, const Unit& u, int wr, int wc, int fr, int fq) const {
;     ...
;             for (int ai = 0; ai < 2; ++ai)
; #pragma unroll
;                 for (int m = 0; m < 4; ++m) { const size_t off = (size_t)(row0 + wr * 64 + fr + ai * 128 + m * 16) * D + col0;
; #pragma unroll
;                     for (int bj = 0; bj < 2; ++bj)
; #pragma unroll
;                         for (int n = 0; n < 2; ++n) { const size_t o2 = off + bj * 128 + n * 16;
;                             const f32x4 r = bf4(*(const u32x2*)(xb + o2)) + gv[bj][n] * acc[ai][bj][m][n];
;                             u32x2 w; w.x = pk2(r[0], r[1]); w.y = pk2(r[2], r[3]); *(u32x2*)(out + o2) = w; }
;                     asm volatile("" ::: "memory"); }
	v_lshlrev_b32_e32 v136, 16, v210
	v_and_b32_e32 v137, 0xffff0000, v210
	v_lshlrev_b32_e32 v134, 16, v211
	v_and_b32_e32 v135, 0xffff0000, v211
	v_pk_fma_f32 v[132:133], v[132:133], v[36:37], v[134:135]
	v_pk_fma_f32 v[130:131], v[130:131], v[34:35], v[136:137]
	s_nop 0
	v_cvt_pk_bf16_f32 v130, v130, v131
	v_cvt_pk_bf16_f32 v131, v132, v133
	global_store_dwordx2 v[146:147], v[130:131], off offset:288
	v_lshl_add_u64 v[130:131], v[146:147], 0, s[8:9]
	s_mov_b32 s8, 0x10000
	v_add_co_u32_e32 v132, vcc, s8, v146
	s_mov_b64 s[8:9], 0x20000
	s_nop 0
	v_addc_co_u32_e32 v133, vcc, 0, v147, vcc
	global_load_dwordx2 v[134:135], v[132:133], off
	global_load_dwordx2 v[206:207], v[130:131], off offset:32
	global_load_dwordx2 v[208:209], v[130:131], off offset:256
	global_load_dwordx2 v[210:211], v[130:131], off offset:288
	s_waitcnt vmcnt(3)
	v_lshlrev_b32_e32 v136, 16, v134
	v_and_b32_e32 v137, 0xffff0000, v134
	v_lshlrev_b32_e32 v134, 16, v135
	v_and_b32_e32 v135, 0xffff0000, v135
	v_pk_fma_f32 v[128:129], v[128:129], v[64:65], v[134:135]
	v_pk_fma_f32 v[126:127], v[126:127], v[62:63], v[136:137]
	s_nop 0
	v_cvt_pk_bf16_f32 v126, v126, v127
	v_cvt_pk_bf16_f32 v127, v128, v129
	global_store_dwordx2 v[132:133], v[126:127], off
	s_waitcnt vmcnt(3)
	v_lshlrev_b32_e32 v128, 16, v206
	v_and_b32_e32 v129, 0xffff0000, v206
	v_lshlrev_b32_e32 v126, 16, v207
	v_and_b32_e32 v127, 0xffff0000, v207
	v_pk_fma_f32 v[124:125], v[124:125], v[56:57], v[126:127]
	v_pk_fma_f32 v[122:123], v[122:123], v[54:55], v[128:129]
	s_nop 0
	v_cvt_pk_bf16_f32 v122, v122, v123
	v_cvt_pk_bf16_f32 v123, v124, v125
	global_store_dwordx2 v[130:131], v[122:123], off offset:32
	s_waitcnt vmcnt(3)
	v_lshlrev_b32_e32 v124, 16, v208
	v_and_b32_e32 v125, 0xffff0000, v208
	v_lshlrev_b32_e32 v122, 16, v209
	v_and_b32_e32 v123, 0xffff0000, v209
	v_pk_fma_f32 v[120:121], v[120:121], v[48:49], v[122:123]
	v_pk_fma_f32 v[118:119], v[118:119], v[46:47], v[124:125]
	s_nop 0
	v_cvt_pk_bf16_f32 v118, v118, v119
	v_cvt_pk_bf16_f32 v119, v120, v121
	global_store_dwordx2 v[130:131], v[118:119], off offset:256
	s_waitcnt vmcnt(3)
	v_lshlrev_b32_e32 v120, 16, v210
	v_and_b32_e32 v121, 0xffff0000, v210
	v_lshlrev_b32_e32 v118, 16, v211
	v_and_b32_e32 v119, 0xffff0000, v211
	v_pk_fma_f32 v[116:117], v[116:117], v[36:37], v[118:119]
	v_pk_fma_f32 v[114:115], v[114:115], v[34:35], v[120:121]
	s_nop 0
	v_cvt_pk_bf16_f32 v114, v114, v115
	v_cvt_pk_bf16_f32 v115, v116, v117
	global_store_dwordx2 v[130:131], v[114:115], off offset:288
	v_lshl_add_u64 v[114:115], v[146:147], 0, s[8:9]
	s_mov_b32 s8, 0x20000
	v_add_co_u32_e32 v116, vcc, s8, v146
	s_mov_b64 s[8:9], 0x30000
	s_nop 0
	v_addc_co_u32_e32 v117, vcc, 0, v147, vcc
	global_load_dwordx2 v[118:119], v[116:117], off
	global_load_dwordx2 v[206:207], v[114:115], off offset:32
	global_load_dwordx2 v[208:209], v[114:115], off offset:256
	global_load_dwordx2 v[210:211], v[114:115], off offset:288
	s_waitcnt vmcnt(3)
	v_lshlrev_b32_e32 v120, 16, v118
	v_and_b32_e32 v121, 0xffff0000, v118
	v_lshlrev_b32_e32 v118, 16, v119
	v_and_b32_e32 v119, 0xffff0000, v119
	v_pk_fma_f32 v[112:113], v[112:113], v[64:65], v[118:119]
	v_pk_fma_f32 v[110:111], v[110:111], v[62:63], v[120:121]
	s_nop 0
	v_cvt_pk_bf16_f32 v110, v110, v111
	v_cvt_pk_bf16_f32 v111, v112, v113
	global_store_dwordx2 v[116:117], v[110:111], off
	s_waitcnt vmcnt(3)
	v_lshlrev_b32_e32 v112, 16, v206
	v_and_b32_e32 v113, 0xffff0000, v206
	v_lshlrev_b32_e32 v110, 16, v207
	v_and_b32_e32 v111, 0xffff0000, v207
	v_pk_fma_f32 v[108:109], v[108:109], v[56:57], v[110:111]
	v_pk_fma_f32 v[106:107], v[106:107], v[54:55], v[112:113]
	s_nop 0
	v_cvt_pk_bf16_f32 v106, v106, v107
	v_cvt_pk_bf16_f32 v107, v108, v109
	global_store_dwordx2 v[114:115], v[106:107], off offset:32
	s_waitcnt vmcnt(3)
	v_lshlrev_b32_e32 v108, 16, v208
	v_and_b32_e32 v109, 0xffff0000, v208
	v_lshlrev_b32_e32 v106, 16, v209
	v_and_b32_e32 v107, 0xffff0000, v209
	v_pk_fma_f32 v[104:105], v[104:105], v[48:49], v[106:107]
	v_pk_fma_f32 v[102:103], v[102:103], v[46:47], v[108:109]
	s_nop 0
	v_cvt_pk_bf16_f32 v102, v102, v103
	v_cvt_pk_bf16_f32 v103, v104, v105
	global_store_dwordx2 v[114:115], v[102:103], off offset:256
	s_waitcnt vmcnt(3)
	v_lshlrev_b32_e32 v104, 16, v210
	v_and_b32_e32 v105, 0xffff0000, v210
	v_lshlrev_b32_e32 v102, 16, v211
	v_and_b32_e32 v103, 0xffff0000, v211
	v_pk_fma_f32 v[100:101], v[100:101], v[36:37], v[102:103]
	v_pk_fma_f32 v[98:99], v[98:99], v[34:35], v[104:105]
	s_nop 0
	v_cvt_pk_bf16_f32 v98, v98, v99
	v_cvt_pk_bf16_f32 v99, v100, v101
	global_store_dwordx2 v[114:115], v[98:99], off offset:288
	v_lshl_add_u64 v[98:99], v[146:147], 0, s[8:9]
	s_mov_b32 s8, 0x30000
	v_add_co_u32_e32 v100, vcc, s8, v146
	s_mov_b64 s[8:9], 0x80000
	s_nop 0
	v_addc_co_u32_e32 v101, vcc, 0, v147, vcc
	global_load_dwordx2 v[102:103], v[100:101], off
	global_load_dwordx2 v[206:207], v[98:99], off offset:32
	global_load_dwordx2 v[208:209], v[98:99], off offset:256
	global_load_dwordx2 v[210:211], v[98:99], off offset:288
	s_waitcnt vmcnt(3)
	v_lshlrev_b32_e32 v104, 16, v102
	v_and_b32_e32 v105, 0xffff0000, v102
	v_lshlrev_b32_e32 v102, 16, v103
	v_and_b32_e32 v103, 0xffff0000, v103
	v_pk_fma_f32 v[96:97], v[96:97], v[64:65], v[102:103]
	v_pk_fma_f32 v[94:95], v[94:95], v[62:63], v[104:105]
	s_nop 0
	v_cvt_pk_bf16_f32 v94, v94, v95
	v_cvt_pk_bf16_f32 v95, v96, v97
	global_store_dwordx2 v[100:101], v[94:95], off
	s_waitcnt vmcnt(3)
	v_lshlrev_b32_e32 v96, 16, v206
	v_and_b32_e32 v97, 0xffff0000, v206
	v_lshlrev_b32_e32 v94, 16, v207
	v_and_b32_e32 v95, 0xffff0000, v207
	v_pk_fma_f32 v[92:93], v[92:93], v[56:57], v[94:95]
	v_pk_fma_f32 v[90:91], v[90:91], v[54:55], v[96:97]
	s_nop 0
	v_cvt_pk_bf16_f32 v90, v90, v91
	v_cvt_pk_bf16_f32 v91, v92, v93
	global_store_dwordx2 v[98:99], v[90:91], off offset:32
	s_waitcnt vmcnt(3)
; DI unsigned pk2(float a, float b) { f32x2 v = {a, b}; bfv2 r = __builtin_convertvector(v, bfv2); return __builtin_bit_cast(unsigned, r); }
;     DI void operator()(AccRef acc, const Unit& u, int wr, int wc, int fr, int fq) const {
;     ...
;             for (int ai = 0; ai < 2; ++ai)
; #pragma unroll
;                 for (int m = 0; m < 4; ++m) { const size_t off = (size_t)(row0 + wr * 64 + fr + ai * 128 + m * 16) * D + col0;
; #pragma unroll
;                     for (int bj = 0; bj < 2; ++bj)
; #pragma unroll
;                         for (int n = 0; n < 2; ++n) { const size_t o2 = off + bj * 128 + n * 16;
;                             const f32x4 r = bf4(*(const u32x2*)(xb + o2)) + gv[bj][n] * acc[ai][bj][m][n];
;                             u32x2 w; w.x = pk2(r[0], r[1]); w.y = pk2(r[2], r[3]); *(u32x2*)(out + o2) = w; }
;                     asm volatile("" ::: "memory"); }
	v_lshlrev_b32_e32 v92, 16, v208
	v_and_b32_e32 v93, 0xffff0000, v208
	v_lshlrev_b32_e32 v90, 16, v209
	v_and_b32_e32 v91, 0xffff0000, v209
	v_pk_fma_f32 v[88:89], v[88:89], v[48:49], v[90:91]
	v_pk_fma_f32 v[86:87], v[86:87], v[46:47], v[92:93]
	s_nop 0
	v_cvt_pk_bf16_f32 v86, v86, v87
	v_cvt_pk_bf16_f32 v87, v88, v89
	global_store_dwordx2 v[98:99], v[86:87], off offset:256
	s_waitcnt vmcnt(3)
	v_lshlrev_b32_e32 v88, 16, v210
	v_and_b32_e32 v89, 0xffff0000, v210
	v_lshlrev_b32_e32 v86, 16, v211
	v_and_b32_e32 v87, 0xffff0000, v211
	v_pk_fma_f32 v[84:85], v[84:85], v[36:37], v[86:87]
	v_pk_fma_f32 v[82:83], v[82:83], v[34:35], v[88:89]
	s_nop 0
	v_cvt_pk_bf16_f32 v82, v82, v83
	v_cvt_pk_bf16_f32 v83, v84, v85
	global_store_dwordx2 v[98:99], v[82:83], off offset:288
	v_lshl_add_u64 v[82:83], v[146:147], 0, s[8:9]
	s_mov_b32 s8, 0x80000
	v_add_co_u32_e32 v84, vcc, s8, v146
	s_mov_b64 s[8:9], 0x90000
	s_nop 0
	v_addc_co_u32_e32 v85, vcc, 0, v147, vcc
	global_load_dwordx2 v[86:87], v[84:85], off
	global_load_dwordx2 v[206:207], v[82:83], off offset:32
	global_load_dwordx2 v[208:209], v[82:83], off offset:256
	global_load_dwordx2 v[210:211], v[82:83], off offset:288
	s_waitcnt vmcnt(3)
	v_lshlrev_b32_e32 v88, 16, v86
	v_and_b32_e32 v89, 0xffff0000, v86
	v_lshlrev_b32_e32 v86, 16, v87
	v_and_b32_e32 v87, 0xffff0000, v87
	v_pk_fma_f32 v[80:81], v[80:81], v[64:65], v[86:87]
	v_pk_fma_f32 v[78:79], v[78:79], v[62:63], v[88:89]
	s_nop 0
	v_cvt_pk_bf16_f32 v78, v78, v79
	v_cvt_pk_bf16_f32 v79, v80, v81
	global_store_dwordx2 v[84:85], v[78:79], off
	s_waitcnt vmcnt(3)
	v_lshlrev_b32_e32 v80, 16, v206
	v_and_b32_e32 v81, 0xffff0000, v206
	v_lshlrev_b32_e32 v78, 16, v207
	v_and_b32_e32 v79, 0xffff0000, v207
	v_pk_fma_f32 v[76:77], v[76:77], v[56:57], v[78:79]
	v_pk_fma_f32 v[74:75], v[74:75], v[54:55], v[80:81]
	s_nop 0
	v_cvt_pk_bf16_f32 v74, v74, v75
	v_cvt_pk_bf16_f32 v75, v76, v77
	global_store_dwordx2 v[82:83], v[74:75], off offset:32
	s_waitcnt vmcnt(3)
	v_lshlrev_b32_e32 v76, 16, v208
	v_and_b32_e32 v77, 0xffff0000, v208
	v_lshlrev_b32_e32 v74, 16, v209
	v_and_b32_e32 v75, 0xffff0000, v209
	v_pk_fma_f32 v[72:73], v[72:73], v[48:49], v[74:75]
	v_pk_fma_f32 v[70:71], v[70:71], v[46:47], v[76:77]
	s_nop 0
	v_cvt_pk_bf16_f32 v70, v70, v71
	v_cvt_pk_bf16_f32 v71, v72, v73
	global_store_dwordx2 v[82:83], v[70:71], off offset:256
	s_waitcnt vmcnt(3)
	v_lshlrev_b32_e32 v72, 16, v210
	v_and_b32_e32 v73, 0xffff0000, v210
	v_lshlrev_b32_e32 v70, 16, v211
	v_and_b32_e32 v71, 0xffff0000, v211
	v_pk_fma_f32 v[68:69], v[68:69], v[36:37], v[70:71]
	v_pk_fma_f32 v[66:67], v[66:67], v[34:35], v[72:73]
	s_nop 0
	v_cvt_pk_bf16_f32 v66, v66, v67
	v_cvt_pk_bf16_f32 v67, v68, v69
	global_store_dwordx2 v[82:83], v[66:67], off offset:288
	v_lshl_add_u64 v[66:67], v[146:147], 0, s[8:9]
	s_mov_b32 s8, 0x90000
	v_add_co_u32_e32 v68, vcc, s8, v146
	s_mov_b64 s[8:9], 0xa0000
	s_nop 0
	v_addc_co_u32_e32 v69, vcc, 0, v147, vcc
	global_load_dwordx2 v[70:71], v[68:69], off
	global_load_dwordx2 v[206:207], v[66:67], off offset:32
	global_load_dwordx2 v[208:209], v[66:67], off offset:256
	global_load_dwordx2 v[210:211], v[66:67], off offset:288
	s_waitcnt vmcnt(3)
	v_lshlrev_b32_e32 v72, 16, v70
	v_and_b32_e32 v73, 0xffff0000, v70
	v_lshlrev_b32_e32 v70, 16, v71
	v_and_b32_e32 v71, 0xffff0000, v71
	v_pk_fma_f32 v[60:61], v[60:61], v[64:65], v[70:71]
	v_pk_fma_f32 v[58:59], v[58:59], v[62:63], v[72:73]
	s_nop 0
	v_cvt_pk_bf16_f32 v58, v58, v59
	v_cvt_pk_bf16_f32 v59, v60, v61
	global_store_dwordx2 v[68:69], v[58:59], off
	s_waitcnt vmcnt(3)
	v_lshlrev_b32_e32 v60, 16, v206
	v_and_b32_e32 v61, 0xffff0000, v206
	v_lshlrev_b32_e32 v58, 16, v207
	v_and_b32_e32 v59, 0xffff0000, v207
	v_pk_fma_f32 v[52:53], v[52:53], v[56:57], v[58:59]
	v_pk_fma_f32 v[50:51], v[50:51], v[54:55], v[60:61]
	s_nop 0
	v_cvt_pk_bf16_f32 v50, v50, v51
	v_cvt_pk_bf16_f32 v51, v52, v53
	global_store_dwordx2 v[66:67], v[50:51], off offset:32
	s_waitcnt vmcnt(3)
	v_lshlrev_b32_e32 v52, 16, v208
	v_and_b32_e32 v53, 0xffff0000, v208
	v_lshlrev_b32_e32 v50, 16, v209
	v_and_b32_e32 v51, 0xffff0000, v209
	v_pk_fma_f32 v[44:45], v[44:45], v[48:49], v[50:51]
	v_pk_fma_f32 v[42:43], v[42:43], v[46:47], v[52:53]
	s_nop 0
	v_cvt_pk_bf16_f32 v42, v42, v43
	v_cvt_pk_bf16_f32 v43, v44, v45
	global_store_dwordx2 v[66:67], v[42:43], off offset:256
	s_waitcnt vmcnt(3)
	v_lshlrev_b32_e32 v44, 16, v210
	v_and_b32_e32 v45, 0xffff0000, v210
	v_lshlrev_b32_e32 v42, 16, v211
	v_and_b32_e32 v43, 0xffff0000, v211
	v_pk_fma_f32 v[40:41], v[40:41], v[36:37], v[42:43]
	v_pk_fma_f32 v[38:39], v[38:39], v[34:35], v[44:45]
	s_nop 0
	v_cvt_pk_bf16_f32 v38, v38, v39
	v_cvt_pk_bf16_f32 v39, v40, v41
	global_store_dwordx2 v[66:67], v[38:39], off offset:288
	v_lshl_add_u64 v[38:39], v[146:147], 0, s[8:9]
	s_mov_b32 s8, 0xa0000
	v_add_co_u32_e32 v40, vcc, s8, v146
	s_mov_b64 s[8:9], 0xb0000
	s_nop 0
	v_addc_co_u32_e32 v41, vcc, 0, v147, vcc
	global_load_dwordx2 v[42:43], v[40:41], off
	global_load_dwordx2 v[206:207], v[38:39], off offset:32
	global_load_dwordx2 v[208:209], v[38:39], off offset:256
	global_load_dwordx2 v[210:211], v[38:39], off offset:288
	s_waitcnt vmcnt(3)
; DI unsigned pk2(float a, float b) { f32x2 v = {a, b}; bfv2 r = __builtin_convertvector(v, bfv2); return __builtin_bit_cast(unsigned, r); }
; template <class Epi, class SchedT>
; DI void gemm_phase(LAS unsigned char* lds, const Gemm g, const SchedT& S, const Epi& E) {
;     ...
;     auto mk_voff = [&]() { int t2 = threadIdx.x; asm volatile("" : "+v"(t2));
; #pragma unroll
;         for (int i = 0; i < 2; ++i) { int R, C; stage_rc(t2 * 16 + i * 8192, R, C); const int Rb = Epi::PERM ? ((R & ~31) + perm32(R & 31)) : R;
;             const int Ra = g.conv ? ((R >> 6) * 126 + (R & 63)) : R;
;             voffA[i] = (unsigned)(Ra * g.lda + C) * 2u; voffB[i] = (unsigned)(Rb * g.ldb + C) * 2u; } };
;     DI void operator()(AccRef acc, const Unit& u, int wr, int wc, int fr, int fq) const {
;     ...
;             for (int ai = 0; ai < 2; ++ai)
; #pragma unroll
;                 for (int m = 0; m < 4; ++m) { const size_t off = (size_t)(row0 + wr * 64 + fr + ai * 128 + m * 16) * D + col0;
; #pragma unroll
;                     for (int bj = 0; bj < 2; ++bj)
; #pragma unroll
;                         for (int n = 0; n < 2; ++n) { const size_t o2 = off + bj * 128 + n * 16;
;                             const f32x4 r = bf4(*(const u32x2*)(xb + o2)) + gv[bj][n] * acc[ai][bj][m][n];
;                             u32x2 w; w.x = pk2(r[0], r[1]); w.y = pk2(r[2], r[3]); *(u32x2*)(out + o2) = w; }
;                     asm volatile("" ::: "memory"); }
	v_lshlrev_b32_e32 v44, 16, v42
	v_and_b32_e32 v45, 0xffff0000, v42
	v_lshlrev_b32_e32 v42, 16, v43
	v_and_b32_e32 v43, 0xffff0000, v43
	v_pk_fma_f32 v[32:33], v[32:33], v[64:65], v[42:43]
	v_pk_fma_f32 v[30:31], v[30:31], v[62:63], v[44:45]
	s_nop 0
	v_cvt_pk_bf16_f32 v30, v30, v31
	v_cvt_pk_bf16_f32 v31, v32, v33
	global_store_dwordx2 v[40:41], v[30:31], off
	s_waitcnt vmcnt(3)
	v_lshlrev_b32_e32 v32, 16, v206
	v_and_b32_e32 v33, 0xffff0000, v206
	v_lshlrev_b32_e32 v30, 16, v207
	v_and_b32_e32 v31, 0xffff0000, v207
	v_pk_fma_f32 v[28:29], v[28:29], v[56:57], v[30:31]
	v_pk_fma_f32 v[26:27], v[26:27], v[54:55], v[32:33]
	s_nop 0
	v_cvt_pk_bf16_f32 v26, v26, v27
	v_cvt_pk_bf16_f32 v27, v28, v29
	global_store_dwordx2 v[38:39], v[26:27], off offset:32
	s_waitcnt vmcnt(3)
	v_lshlrev_b32_e32 v28, 16, v208
	v_and_b32_e32 v29, 0xffff0000, v208
	v_lshlrev_b32_e32 v26, 16, v209
	v_and_b32_e32 v27, 0xffff0000, v209
	v_pk_fma_f32 v[24:25], v[24:25], v[48:49], v[26:27]
	v_pk_fma_f32 v[22:23], v[22:23], v[46:47], v[28:29]
	s_nop 0
	v_cvt_pk_bf16_f32 v22, v22, v23
	v_cvt_pk_bf16_f32 v23, v24, v25
	global_store_dwordx2 v[38:39], v[22:23], off offset:256
	s_waitcnt vmcnt(3)
	v_lshlrev_b32_e32 v24, 16, v210
	v_and_b32_e32 v25, 0xffff0000, v210
	v_lshlrev_b32_e32 v22, 16, v211
	v_and_b32_e32 v23, 0xffff0000, v211
	v_pk_fma_f32 v[20:21], v[20:21], v[36:37], v[22:23]
	v_pk_fma_f32 v[18:19], v[18:19], v[34:35], v[24:25]
	s_nop 0
	v_cvt_pk_bf16_f32 v18, v18, v19
	v_cvt_pk_bf16_f32 v19, v20, v21
	global_store_dwordx2 v[38:39], v[18:19], off offset:288
	v_lshl_add_u64 v[18:19], v[146:147], 0, s[8:9]
	s_mov_b32 s8, 0xb0000
	v_add_co_u32_e32 v20, vcc, s8, v146
	s_mov_b64 s[8:9], -1
	s_nop 0
	v_addc_co_u32_e32 v21, vcc, 0, v147, vcc
	global_load_dwordx2 v[22:23], v[20:21], off
	global_load_dwordx2 v[206:207], v[18:19], off offset:32
	global_load_dwordx2 v[208:209], v[18:19], off offset:256
	global_load_dwordx2 v[210:211], v[18:19], off offset:288
	s_and_b64 vcc, exec, s[2:3]
	s_waitcnt vmcnt(3)
	v_lshlrev_b32_e32 v24, 16, v22
	v_and_b32_e32 v25, 0xffff0000, v22
	v_lshlrev_b32_e32 v22, 16, v23
	v_and_b32_e32 v23, 0xffff0000, v23
	v_pk_fma_f32 v[16:17], v[16:17], v[64:65], v[22:23]
	v_pk_fma_f32 v[14:15], v[14:15], v[62:63], v[24:25]
	s_nop 0
	v_cvt_pk_bf16_f32 v14, v14, v15
	v_cvt_pk_bf16_f32 v15, v16, v17
	global_store_dwordx2 v[20:21], v[14:15], off
	s_waitcnt vmcnt(3)
	v_lshlrev_b32_e32 v16, 16, v206
	v_and_b32_e32 v17, 0xffff0000, v206
	v_lshlrev_b32_e32 v14, 16, v207
	v_and_b32_e32 v15, 0xffff0000, v207
	v_pk_fma_f32 v[12:13], v[12:13], v[56:57], v[14:15]
	v_pk_fma_f32 v[10:11], v[10:11], v[54:55], v[16:17]
	s_nop 0
	v_cvt_pk_bf16_f32 v10, v10, v11
	v_cvt_pk_bf16_f32 v11, v12, v13
	global_store_dwordx2 v[18:19], v[10:11], off offset:32
	s_waitcnt vmcnt(3)
	v_lshlrev_b32_e32 v12, 16, v208
	v_and_b32_e32 v13, 0xffff0000, v208
	v_lshlrev_b32_e32 v10, 16, v209
	v_and_b32_e32 v11, 0xffff0000, v209
	v_pk_fma_f32 v[8:9], v[8:9], v[48:49], v[10:11]
	v_pk_fma_f32 v[6:7], v[6:7], v[46:47], v[12:13]
	s_nop 0
	v_cvt_pk_bf16_f32 v6, v6, v7
	v_cvt_pk_bf16_f32 v7, v8, v9
	global_store_dwordx2 v[18:19], v[6:7], off offset:256
	s_waitcnt vmcnt(3)
	v_lshlrev_b32_e32 v8, 16, v210
	v_and_b32_e32 v9, 0xffff0000, v210
	v_lshlrev_b32_e32 v6, 16, v211
	v_and_b32_e32 v7, 0xffff0000, v211
	v_pk_fma_f32 v[4:5], v[4:5], v[36:37], v[6:7]
	v_pk_fma_f32 v[2:3], v[2:3], v[34:35], v[8:9]
	s_nop 0
	v_cvt_pk_bf16_f32 v2, v2, v3
	v_cvt_pk_bf16_f32 v3, v4, v5
	global_store_dwordx2 v[18:19], v[2:3], off offset:288
	s_cbranch_vccz .LBB0_1697
	v_mov_b32_e32 v0, v192
	s_mov_b64 s[8:9], 0
	v_ashrrev_i32_e32 v3, 31, v0
	v_lshrrev_b32_e32 v3, 26, v3
	v_lshlrev_b32_e32 v2, 4, v0
	v_add_u32_e32 v3, v0, v3
	v_bfe_i32 v0, v0, 27, 1
	v_lshrrev_b32_e32 v0, 22, v0
	v_add_u32_e32 v0, v2, v0
	v_and_b32_e32 v0, 0xfffffc00, v0
	v_sub_u32_e32 v0, v2, v0
	v_lshrrev_b32_e32 v4, 4, v0
	v_bitop3_b32 v0, v4, v0, 32 bitop3:0x6c
	v_ashrrev_i32_e32 v5, 31, v0
	v_ashrrev_i32_e32 v3, 6, v3
	v_lshrrev_b32_e32 v5, 26, v5
	v_lshlrev_b32_e32 v4, 3, v3
	v_add_u32_e32 v5, v0, v5
	v_and_b32_e32 v4, 0x7ffff0, v4
	v_lshrrev_b32_e32 v6, 6, v5
	v_and_b32_e32 v5, 0xc0, v5
	v_add_u32_e32 v4, v6, v4
	v_sub_u32_e32 v0, v0, v5
	v_lshlrev_b32_e32 v3, 5, v3
	v_ashrrev_i16_sdwa v0, v200, sext(v0) dst_sel:DWORD dst_unused:UNUSED_PAD src0_sel:DWORD src1_sel:BYTE_0
	v_mul_lo_u32 v4, v4, s45
	v_bfe_i32 v0, v0, 0, 16
	v_and_or_b32 v3, v3, 32, v4
	v_add_u32_e32 v2, 0x2000, v2
	v_add_lshl_u32 v0, v3, v0, 1
	v_ashrrev_i32_e32 v3, 31, v2
	v_lshrrev_b32_e32 v3, 22, v3
	v_add_u32_e32 v3, v2, v3
	v_ashrrev_i32_e32 v3, 10, v3
	v_mul_i32_i24_e32 v4, 0x400, v3
	v_sub_u32_e32 v2, v2, v4
	v_lshrrev_b32_e32 v4, 4, v2
	v_bitop3_b32 v2, v4, v2, 32 bitop3:0x6c
	v_ashrrev_i32_e32 v5, 31, v2
	v_lshrrev_b32_e32 v5, 26, v5
	v_lshlrev_b32_e32 v4, 3, v3
	v_add_u32_e32 v5, v2, v5
	v_and_b32_e32 v4, 0x7ffff0, v4
	v_lshrrev_b32_e32 v6, 6, v5
	v_and_b32_e32 v5, 0xc0, v5
	v_add_u32_e32 v4, v6, v4
	v_sub_u32_e32 v2, v2, v5
	v_lshlrev_b32_e32 v3, 5, v3
	v_ashrrev_i16_sdwa v2, v200, sext(v2) dst_sel:DWORD dst_unused:UNUSED_PAD src0_sel:DWORD src1_sel:BYTE_0
	v_mul_lo_u32 v4, v4, s45
	v_bfe_i32 v2, v2, 0, 16
	v_and_or_b32 v3, v3, 32, v4
	v_add_lshl_u32 v34, v3, v2, 1
	s_branch .LBB0_1697
